# v37 with non-temporal instead of write-through stores for the SGU and DFT stage-2 outputs (probe: -3.7 and -1.3 us per phase)
# speedup vs baseline: 1.0183x; 1.0008x over previous
.LBB0_117:
	s_ashr_i32 s8, s22, 3
	s_abs_i32 s10, s8
	s_mul_hi_u32 s11, s10, s13
	s_mul_i32 s14, s11, s2
	s_sub_i32 s10, s10, s14
	s_ashr_i32 s9, s22, 31
	s_add_i32 s14, s11, 1
	s_sub_i32 s15, s10, s2
	s_cmp_ge_u32 s10, s2
	s_cselect_b32 s11, s14, s11
	s_cselect_b32 s10, s15, s10
	s_add_i32 s14, s11, 1
	s_cmp_ge_u32 s10, s2
	s_cselect_b32 s10, s14, s11
	s_xor_b32 s10, s10, s9
	s_sub_i32 s10, s10, s9
	s_mul_i32 s9, s10, s2
	s_sub_i32 s14, s8, s9
	s_mulk_i32 s8, 0x101
	s_ashr_i32 s9, s8, 31
	s_lshl_b64 s[8:9], s[8:9], 11
	s_add_u32 s11, s4, s8
	s_addc_u32 s15, s5, s9
	s_and_b32 s8, s18, 0x380
	s_lshl_b32 s8, s8, 1
	s_add_u32 s24, s11, s8
	s_addc_u32 s25, s15, 0
	v_lshl_add_u64 v[0:1], s[24:25], 0, v[154:155]
	v_lshl_add_u64 v[2:3], v[0:1], 0, v[38:39]
	global_load_dwordx2 v[72:73], v[2:3], off
	v_lshl_add_u64 v[2:3], v[0:1], 0, v[40:41]
	global_load_dwordx2 v[74:75], v[2:3], off
	v_lshl_add_u64 v[2:3], v[0:1], 0, v[42:43]
	global_load_dwordx2 v[76:77], v[2:3], off
	v_lshl_add_u64 v[2:3], v[0:1], 0, v[44:45]
	global_load_dwordx2 v[78:79], v[2:3], off
	v_lshl_add_u64 v[2:3], v[0:1], 0, v[46:47]
	global_load_dwordx2 v[80:81], v[2:3], off
	v_lshl_add_u64 v[2:3], v[0:1], 0, v[48:49]
	global_load_dwordx2 v[82:83], v[2:3], off
	v_lshl_add_u64 v[2:3], v[0:1], 0, v[50:51]
	global_load_dwordx2 v[84:85], v[2:3], off
	v_lshl_add_u64 v[2:3], v[0:1], 0, v[52:53]
	global_load_dwordx2 v[86:87], v[2:3], off
	v_lshl_add_u64 v[2:3], v[0:1], 0, v[54:55]
	global_load_dwordx2 v[88:89], v[2:3], off
	v_lshl_add_u64 v[2:3], v[0:1], 0, v[56:57]
	global_load_dwordx2 v[102:103], v[2:3], off
	v_lshl_add_u64 v[2:3], v[0:1], 0, v[58:59]
	global_load_dwordx2 v[104:105], v[2:3], off
	v_lshl_add_u64 v[2:3], v[0:1], 0, v[60:61]
	global_load_dwordx2 v[106:107], v[2:3], off
	v_lshl_add_u64 v[2:3], v[0:1], 0, v[62:63]
	global_load_dwordx2 v[108:109], v[2:3], off
	v_lshl_add_u64 v[2:3], v[0:1], 0, v[64:65]
	global_load_dwordx2 v[110:111], v[2:3], off
	v_lshl_add_u64 v[2:3], v[0:1], 0, v[66:67]
	global_load_dwordx2 v[112:113], v[2:3], off
	v_lshl_add_u64 v[0:1], v[0:1], 0, v[68:69]
	global_load_dwordx2 v[114:115], v[0:1], off
	s_ashr_i32 s11, s10, 31
	s_lshl_b64 s[10:11], s[10:11], s3
	s_ashr_i32 s15, s14, 31
	s_add_u32 s10, s10, s14
	v_add_u32_e32 v71, v90, v100
	s_addc_u32 s11, s11, s15
	s_mov_b32 s9, s96
	s_waitcnt vmcnt(14)
	ds_write2st64_b64 v71, v[72:73], v[74:75] offset1:9
	s_waitcnt vmcnt(12)
	ds_write2st64_b64 v71, v[76:77], v[78:79] offset0:18 offset1:27
	s_waitcnt vmcnt(10)
	ds_write2st64_b64 v71, v[80:81], v[82:83] offset0:36 offset1:45
	s_waitcnt vmcnt(8)
	ds_write2st64_b64 v71, v[84:85], v[86:87] offset0:54 offset1:63
	s_waitcnt vmcnt(6)
	ds_write2st64_b64 v71, v[88:89], v[102:103] offset0:72 offset1:81
	s_waitcnt vmcnt(4)
	ds_write2st64_b64 v71, v[104:105], v[106:107] offset0:90 offset1:99
	s_waitcnt vmcnt(2)
	ds_write2st64_b64 v71, v[108:109], v[110:111] offset0:108 offset1:117
	s_waitcnt vmcnt(1)
	ds_write_b64 v71, v[112:113] offset:64512
	s_waitcnt vmcnt(0)
	ds_write_b64 v101, v[114:115] offset:64512
	v_lshl_add_u64 v[72:73], s[10:11], 0, v[36:37]
	v_mov_b64_e32 v[74:75], s[92:93]
	v_mad_u64_u32 v[74:75], s[10:11], v72, s33, v[74:75]
	v_mad_i32_i24 v75, v73, s33, v75
	v_lshl_add_u64 v[74:75], v[74:75], 0, s[8:9]
	v_mov_b32_e32 v71, v155
	v_lshl_add_u64 v[74:75], v[74:75], 0, v[70:71]
	v_lshl_add_u64 v[102:103], v[74:75], 0, s[72:73]
	v_add_co_u32_e32 v74, vcc, s69, v74
	s_waitcnt lgkmcnt(0)
	s_nop 0
	v_addc_co_u32_e32 v75, vcc, 0, v75, vcc
	s_nop 0
	v_readfirstlane_b32 s98, v74
	v_readfirstlane_b32 s99, v75
	s_nop 4
	global_load_dwordx4 v[74:77], v184, s[98:99]
	s_add_u32 s98, s98, s100
	s_addc_u32 s99, s99, 0
	global_load_dwordx4 v[78:81], v184, s[98:99]
	s_add_u32 s98, s98, s100
	s_addc_u32 s99, s99, 0
	global_load_dwordx4 v[82:85], v184, s[98:99]
	s_add_u32 s98, s98, s100
	s_addc_u32 s99, s99, 0
	global_load_dwordx4 v[86:89], v184, s[98:99]
	s_barrier
	ds_read_b64_tr_b16 v[104:105], v91 offset:4608
	ds_read_b64_tr_b16 v[102:103], v91
	ds_read_b64_tr_b16 v[106:107], v91 offset:32
	ds_read_b64_tr_b16 v[108:109], v91 offset:4640
	ds_read_b64_tr_b16 v[110:111], v91 offset:64
	ds_read_b64_tr_b16 v[112:113], v91 offset:4672
	ds_read_b64_tr_b16 v[114:115], v91 offset:96
	ds_read_b64_tr_b16 v[116:117], v91 offset:4704
	ds_read_b64_tr_b16 v[118:119], v91 offset:128
	ds_read_b64_tr_b16 v[120:121], v91 offset:4736
	ds_read_b64_tr_b16 v[122:123], v91 offset:160
	ds_read_b64_tr_b16 v[124:125], v91 offset:4768
	ds_read_b64_tr_b16 v[126:127], v91 offset:192
	ds_read_b64_tr_b16 v[128:129], v91 offset:4800
	ds_read_b64_tr_b16 v[130:131], v91 offset:224
	ds_read_b64_tr_b16 v[132:133], v91 offset:4832
	ds_read_b64_tr_b16 v[134:135], v91 offset:9216
	ds_read_b64_tr_b16 v[136:137], v91 offset:13824
	ds_read_b64_tr_b16 v[138:139], v91 offset:9248
	ds_read_b64_tr_b16 v[140:141], v91 offset:13856
	ds_read_b64_tr_b16 v[142:143], v91 offset:9280
	ds_read_b64_tr_b16 v[144:145], v91 offset:13888
	ds_read_b64_tr_b16 v[146:147], v91 offset:9312
	ds_read_b64_tr_b16 v[148:149], v91 offset:13920
	ds_read_b64_tr_b16 v[156:157], v91 offset:9344
	ds_read_b64_tr_b16 v[158:159], v91 offset:13952
	ds_read_b64_tr_b16 v[160:161], v91 offset:9376
	ds_read_b64_tr_b16 v[162:163], v91 offset:13984
	ds_read_b64_tr_b16 v[164:165], v91 offset:9408
	ds_read_b64_tr_b16 v[166:167], v91 offset:14016
	ds_read_b64_tr_b16 v[168:169], v91 offset:9440
	ds_read_b64_tr_b16 v[170:171], v91 offset:14048
	s_waitcnt vmcnt(22) lgkmcnt(14)
	v_mfma_f32_16x16x32_bf16 v[102:105], v[102:105], v[238:241], 0
	v_mfma_f32_16x16x32_bf16 v[106:109], v[106:109], v[238:241], 0
	v_mfma_f32_16x16x32_bf16 v[110:113], v[110:113], v[238:241], 0
	v_mfma_f32_16x16x32_bf16 v[114:117], v[114:117], v[238:241], 0
	v_mfma_f32_16x16x32_bf16 v[118:121], v[118:121], v[238:241], 0
	v_mfma_f32_16x16x32_bf16 v[122:125], v[122:125], v[238:241], 0
	v_mfma_f32_16x16x32_bf16 v[126:129], v[126:129], v[238:241], 0
	v_mfma_f32_16x16x32_bf16 v[28:31], v[130:133], v[238:241], 0
	ds_read_b64_tr_b16 v[130:131], v91 offset:18432
	ds_read_b64_tr_b16 v[172:173], v91 offset:18464
	ds_read_b64_tr_b16 v[176:177], v91 offset:18496
	ds_read_b64_tr_b16 v[180:181], v91 offset:18528
	ds_read_b64_tr_b16 v[132:133], v91 offset:23040
	ds_read_b64_tr_b16 v[174:175], v91 offset:23072
	ds_read_b64_tr_b16 v[178:179], v91 offset:23104
	ds_read_b64_tr_b16 v[182:183], v91 offset:23136
	ds_read_b64_tr_b16 v[188:189], v91 offset:18560
	ds_read_b64_tr_b16 v[192:193], v91 offset:18592
	ds_read_b64_tr_b16 v[202:203], v91 offset:18624
	ds_read_b64_tr_b16 v[206:207], v91 offset:18656
	ds_read_b64_tr_b16 v[190:191], v91 offset:23168
	ds_read_b64_tr_b16 v[194:195], v91 offset:23200
	ds_read_b64_tr_b16 v[204:205], v91 offset:23232
	ds_read_b64_tr_b16 v[208:209], v91 offset:23264
	s_waitcnt vmcnt(20)
	v_mfma_f32_16x16x32_bf16 v[102:105], v[134:137], v[234:237], v[102:105]
	s_waitcnt lgkmcnt(14)
	v_mfma_f32_16x16x32_bf16 v[106:109], v[138:141], v[234:237], v[106:109]
	v_mfma_f32_16x16x32_bf16 v[110:113], v[142:145], v[234:237], v[110:113]
	v_mfma_f32_16x16x32_bf16 v[114:117], v[146:149], v[234:237], v[114:117]
	v_mfma_f32_16x16x32_bf16 v[118:121], v[156:159], v[234:237], v[118:121]
	v_mfma_f32_16x16x32_bf16 v[122:125], v[160:163], v[234:237], v[122:125]
	v_mfma_f32_16x16x32_bf16 v[126:129], v[164:167], v[234:237], v[126:129]
	v_mfma_f32_16x16x32_bf16 v[24:27], v[168:171], v[234:237], v[28:31]
	s_nop 2
	ds_read_b64_tr_b16 v[28:29], v91 offset:27648
	ds_read_b64_tr_b16 v[134:135], v91 offset:27680
	ds_read_b64_tr_b16 v[138:139], v91 offset:27712
	ds_read_b64_tr_b16 v[142:143], v91 offset:27744
	ds_read_b64_tr_b16 v[30:31], v91 offset:32256
	ds_read_b64_tr_b16 v[136:137], v91 offset:32288
	ds_read_b64_tr_b16 v[140:141], v91 offset:32320
	ds_read_b64_tr_b16 v[144:145], v91 offset:32352
	ds_read_b64_tr_b16 v[146:147], v91 offset:27776
	ds_read_b64_tr_b16 v[156:157], v91 offset:27808
	ds_read_b64_tr_b16 v[160:161], v91 offset:27840
	ds_read_b64_tr_b16 v[164:165], v91 offset:27872
	ds_read_b64_tr_b16 v[148:149], v91 offset:32384
	ds_read_b64_tr_b16 v[158:159], v91 offset:32416
	ds_read_b64_tr_b16 v[162:163], v91 offset:32448
	ds_read_b64_tr_b16 v[166:167], v91 offset:32480
	s_waitcnt vmcnt(18) lgkmcnt(14)
	v_mfma_f32_16x16x32_bf16 v[102:105], v[130:133], v[230:233], v[102:105]
	v_mfma_f32_16x16x32_bf16 v[106:109], v[172:175], v[230:233], v[106:109]
	v_mfma_f32_16x16x32_bf16 v[110:113], v[176:179], v[230:233], v[110:113]
	v_mfma_f32_16x16x32_bf16 v[114:117], v[180:183], v[230:233], v[114:117]
	v_mfma_f32_16x16x32_bf16 v[118:121], v[188:191], v[230:233], v[118:121]
	v_mfma_f32_16x16x32_bf16 v[122:125], v[192:195], v[230:233], v[122:125]
	v_mfma_f32_16x16x32_bf16 v[126:129], v[202:205], v[230:233], v[126:129]
	v_mfma_f32_16x16x32_bf16 v[20:23], v[206:209], v[230:233], v[24:27]
	s_nop 2
	ds_read_b64_tr_b16 v[24:25], v91 offset:36864
	ds_read_b64_tr_b16 v[130:131], v91 offset:36896
	ds_read_b64_tr_b16 v[168:169], v91 offset:36928
	ds_read_b64_tr_b16 v[172:173], v91 offset:36960
	ds_read_b64_tr_b16 v[26:27], v91 offset:41472
	ds_read_b64_tr_b16 v[132:133], v91 offset:41504
	ds_read_b64_tr_b16 v[170:171], v91 offset:41536
	ds_read_b64_tr_b16 v[174:175], v91 offset:41568
	ds_read_b64_tr_b16 v[176:177], v91 offset:36992
	ds_read_b64_tr_b16 v[180:181], v91 offset:37024
	ds_read_b64_tr_b16 v[188:189], v91 offset:37056
	ds_read_b64_tr_b16 v[192:193], v91 offset:37088
	ds_read_b64_tr_b16 v[178:179], v91 offset:41600
	ds_read_b64_tr_b16 v[182:183], v91 offset:41632
	ds_read_b64_tr_b16 v[190:191], v91 offset:41664
	ds_read_b64_tr_b16 v[194:195], v91 offset:41696
	s_waitcnt vmcnt(16) lgkmcnt(14)
	v_mfma_f32_16x16x32_bf16 v[28:31], v[28:31], v[226:229], v[102:105]
	v_mfma_f32_16x16x32_bf16 v[102:105], v[134:137], v[226:229], v[106:109]
	v_mfma_f32_16x16x32_bf16 v[106:109], v[138:141], v[226:229], v[110:113]
	v_mfma_f32_16x16x32_bf16 v[110:113], v[142:145], v[226:229], v[114:117]
	v_mfma_f32_16x16x32_bf16 v[114:117], v[146:149], v[226:229], v[118:121]
	v_mfma_f32_16x16x32_bf16 v[118:121], v[156:159], v[226:229], v[122:125]
	v_mfma_f32_16x16x32_bf16 v[122:125], v[160:163], v[226:229], v[126:129]
	v_mfma_f32_16x16x32_bf16 v[16:19], v[164:167], v[226:229], v[20:23]
	s_nop 2
	ds_read_b64_tr_b16 v[20:21], v91 offset:46080
	ds_read_b64_tr_b16 v[126:127], v91 offset:46112
	ds_read_b64_tr_b16 v[134:135], v91 offset:46144
	ds_read_b64_tr_b16 v[138:139], v91 offset:46176
	ds_read_b64_tr_b16 v[22:23], v91 offset:50688
	ds_read_b64_tr_b16 v[128:129], v91 offset:50720
	ds_read_b64_tr_b16 v[136:137], v91 offset:50752
	ds_read_b64_tr_b16 v[140:141], v91 offset:50784
	ds_read_b64_tr_b16 v[142:143], v91 offset:46208
	ds_read_b64_tr_b16 v[146:147], v91 offset:46240
	ds_read_b64_tr_b16 v[156:157], v91 offset:46272
	ds_read_b64_tr_b16 v[160:161], v91 offset:46304
	ds_read_b64_tr_b16 v[144:145], v91 offset:50816
	ds_read_b64_tr_b16 v[148:149], v91 offset:50848
	ds_read_b64_tr_b16 v[158:159], v91 offset:50880
	ds_read_b64_tr_b16 v[162:163], v91 offset:50912
	s_waitcnt vmcnt(14) lgkmcnt(14)
	v_mfma_f32_16x16x32_bf16 v[24:27], v[24:27], v[222:225], v[28:31]
	v_mfma_f32_16x16x32_bf16 v[28:31], v[130:133], v[222:225], v[102:105]
	v_mfma_f32_16x16x32_bf16 v[102:105], v[168:171], v[222:225], v[106:109]
	v_mfma_f32_16x16x32_bf16 v[106:109], v[172:175], v[222:225], v[110:113]
	v_mfma_f32_16x16x32_bf16 v[110:113], v[176:179], v[222:225], v[114:117]
	v_mfma_f32_16x16x32_bf16 v[114:117], v[180:183], v[222:225], v[118:121]
	v_mfma_f32_16x16x32_bf16 v[118:121], v[188:191], v[222:225], v[122:125]
	v_mfma_f32_16x16x32_bf16 v[12:15], v[192:195], v[222:225], v[16:19]
	s_nop 2
	ds_read_b64_tr_b16 v[16:17], v91 offset:55296
	ds_read_b64_tr_b16 v[122:123], v91 offset:55328
	ds_read_b64_tr_b16 v[130:131], v91 offset:55360
	ds_read_b64_tr_b16 v[164:165], v91 offset:55392
	ds_read_b64_tr_b16 v[18:19], v91 offset:59904
	ds_read_b64_tr_b16 v[124:125], v91 offset:59936
	ds_read_b64_tr_b16 v[132:133], v91 offset:59968
	ds_read_b64_tr_b16 v[166:167], v91 offset:60000
	ds_read_b64_tr_b16 v[168:169], v91 offset:55424
	ds_read_b64_tr_b16 v[172:173], v91 offset:55456
	ds_read_b64_tr_b16 v[176:177], v91 offset:55488
	ds_read_b64_tr_b16 v[180:181], v91 offset:55520
	ds_read_b64_tr_b16 v[170:171], v91 offset:60032
	ds_read_b64_tr_b16 v[174:175], v91 offset:60064
	ds_read_b64_tr_b16 v[178:179], v91 offset:60096
	ds_read_b64_tr_b16 v[182:183], v91 offset:60128
	s_waitcnt vmcnt(12) lgkmcnt(14)
	v_mfma_f32_16x16x32_bf16 v[20:23], v[20:23], v[218:221], v[24:27]
	v_mfma_f32_16x16x32_bf16 v[24:27], v[126:129], v[218:221], v[28:31]
	v_mfma_f32_16x16x32_bf16 v[28:31], v[134:137], v[218:221], v[102:105]
	v_mfma_f32_16x16x32_bf16 v[102:105], v[138:141], v[218:221], v[106:109]
	v_mfma_f32_16x16x32_bf16 v[106:109], v[142:145], v[218:221], v[110:113]
	v_mfma_f32_16x16x32_bf16 v[110:113], v[146:149], v[218:221], v[114:117]
	v_mfma_f32_16x16x32_bf16 v[114:117], v[156:159], v[218:221], v[118:121]
	v_mfma_f32_16x16x32_bf16 v[8:11], v[160:163], v[218:221], v[12:15]
	s_nop 2
	ds_read_b64_tr_b16 v[12:13], v91 offset:64512
	ds_read_b64_tr_b16 v[118:119], v91 offset:64544
	ds_read_b64_tr_b16 v[126:127], v91 offset:64576
	ds_read_b64_tr_b16 v[134:135], v91 offset:64608
	ds_read_b64_tr_b16 v[14:15], v92
	ds_read_b64_tr_b16 v[120:121], v93
	ds_read_b64_tr_b16 v[128:129], v94
	ds_read_b64_tr_b16 v[136:137], v95
	ds_read_b64_tr_b16 v[138:139], v91 offset:64640
	ds_read_b64_tr_b16 v[142:143], v91 offset:64672
	ds_read_b64_tr_b16 v[146:147], v91 offset:64704
	ds_read_b64_tr_b16 v[156:157], v91 offset:64736
	ds_read_b64_tr_b16 v[140:141], v96
	ds_read_b64_tr_b16 v[144:145], v97
	ds_read_b64_tr_b16 v[148:149], v98
	ds_read_b64_tr_b16 v[158:159], v99
	s_waitcnt vmcnt(10) lgkmcnt(14)
	v_mfma_f32_16x16x32_bf16 v[16:19], v[16:19], v[214:217], v[20:23]
	v_mfma_f32_16x16x32_bf16 v[20:23], v[122:125], v[214:217], v[24:27]
	v_mfma_f32_16x16x32_bf16 v[24:27], v[130:133], v[214:217], v[28:31]
	v_mfma_f32_16x16x32_bf16 v[28:31], v[164:167], v[214:217], v[102:105]
	v_mfma_f32_16x16x32_bf16 v[102:105], v[168:171], v[214:217], v[106:109]
	v_mfma_f32_16x16x32_bf16 v[106:109], v[172:175], v[214:217], v[110:113]
	v_mfma_f32_16x16x32_bf16 v[110:113], v[176:179], v[214:217], v[114:117]
	v_mfma_f32_16x16x32_bf16 v[4:7], v[180:183], v[214:217], v[8:11]
	s_waitcnt vmcnt(8) lgkmcnt(11)
	v_mfma_f32_16x16x32_bf16 v[8:11], v[12:15], v[210:213], v[16:19]
	s_waitcnt lgkmcnt(10)
	v_mfma_f32_16x16x32_bf16 v[12:15], v[118:121], v[210:213], v[20:23]
	s_waitcnt lgkmcnt(9)
	v_mfma_f32_16x16x32_bf16 v[16:19], v[126:129], v[210:213], v[24:27]
	s_waitcnt lgkmcnt(8)
	v_mfma_f32_16x16x32_bf16 v[20:23], v[134:137], v[210:213], v[28:31]
	s_waitcnt lgkmcnt(3)
	v_mfma_f32_16x16x32_bf16 v[24:27], v[138:141], v[210:213], v[102:105]
	s_waitcnt lgkmcnt(2)
	v_mfma_f32_16x16x32_bf16 v[28:31], v[142:145], v[210:213], v[106:109]
	s_waitcnt lgkmcnt(1)
	v_mfma_f32_16x16x32_bf16 v[102:105], v[146:149], v[210:213], v[110:113]
	s_waitcnt lgkmcnt(0)
	v_mfma_f32_16x16x32_bf16 v[0:3], v[156:159], v[210:213], v[4:7]
	s_nop 2
	s_waitcnt vmcnt(0)
	ds_write_b128 v185, v[74:77]
	ds_write_b128 v185, v[78:81] offset:1152
	ds_write_b128 v185, v[82:85] offset:2304
	ds_write_b128 v185, v[86:89] offset:3456
	s_waitcnt lgkmcnt(0)
	ds_read_b64 v[88:89], v186
	ds_read_b64 v[86:87], v186 offset:32
	ds_read_b64 v[84:85], v186 offset:64
	ds_read_b64 v[82:83], v186 offset:96
	ds_read_b64 v[80:81], v186 offset:128
	ds_read_b64 v[78:79], v186 offset:160
	ds_read_b64 v[76:77], v186 offset:192
	ds_read_b64 v[74:75], v186 offset:224
	s_waitcnt lgkmcnt(0)
	v_mov_b64_e32 v[4:5], s[38:39]
	v_mad_u64_u32 v[4:5], s[10:11], v72, s34, v[4:5]
	v_pk_mul_f32 v[6:7], v[32:33], v[8:9]
	s_waitcnt vmcnt(7)
	v_lshlrev_b32_e32 v8, 16, v88
	v_and_b32_e32 v9, 0xffff0000, v88
	v_mad_i32_i24 v5, v73, s34, v5
	v_pk_mul_f32 v[6:7], v[6:7], v[8:9]
	v_pk_mul_f32 v[8:9], v[32:33], v[10:11]
	v_lshlrev_b32_e32 v10, 16, v89
	v_and_b32_e32 v11, 0xffff0000, v89
	v_lshl_add_u64 v[4:5], v[4:5], 0, s[8:9]
	v_pk_mul_f32 v[8:9], v[8:9], v[10:11]
	v_lshl_add_u64 v[4:5], v[4:5], 0, v[70:71]
	v_cvt_pk_bf16_f32 v6, v6, v7
	v_cvt_pk_bf16_f32 v7, v8, v9
	ds_write_b64 v186, v[6:7]
	v_pk_mul_f32 v[6:7], v[32:33], v[12:13]
	s_waitcnt vmcnt(7)
	v_lshlrev_b32_e32 v8, 16, v86
	v_and_b32_e32 v9, 0xffff0000, v86
	v_pk_mul_f32 v[6:7], v[6:7], v[8:9]
	v_pk_mul_f32 v[8:9], v[32:33], v[14:15]
	v_lshlrev_b32_e32 v10, 16, v87
	v_and_b32_e32 v11, 0xffff0000, v87
	v_pk_mul_f32 v[8:9], v[8:9], v[10:11]
	v_cvt_pk_bf16_f32 v6, v6, v7
	v_cvt_pk_bf16_f32 v7, v8, v9
	ds_write_b64 v186, v[6:7] offset:32
	v_pk_mul_f32 v[6:7], v[32:33], v[16:17]
	s_waitcnt vmcnt(7)
	v_lshlrev_b32_e32 v8, 16, v84
	v_and_b32_e32 v9, 0xffff0000, v84
	v_pk_mul_f32 v[6:7], v[6:7], v[8:9]
	v_pk_mul_f32 v[8:9], v[32:33], v[18:19]
	v_lshlrev_b32_e32 v10, 16, v85
	v_and_b32_e32 v11, 0xffff0000, v85
	v_pk_mul_f32 v[8:9], v[8:9], v[10:11]
	v_cvt_pk_bf16_f32 v6, v6, v7
	v_cvt_pk_bf16_f32 v7, v8, v9
	ds_write_b64 v186, v[6:7] offset:64
	v_pk_mul_f32 v[6:7], v[32:33], v[20:21]
	s_waitcnt vmcnt(7)
	v_lshlrev_b32_e32 v8, 16, v82
	v_and_b32_e32 v9, 0xffff0000, v82
	v_pk_mul_f32 v[6:7], v[6:7], v[8:9]
	v_pk_mul_f32 v[8:9], v[32:33], v[22:23]
	v_lshlrev_b32_e32 v10, 16, v83
	v_and_b32_e32 v11, 0xffff0000, v83
	v_pk_mul_f32 v[8:9], v[8:9], v[10:11]
	v_cvt_pk_bf16_f32 v6, v6, v7
	v_cvt_pk_bf16_f32 v7, v8, v9
	ds_write_b64 v186, v[6:7] offset:96
	v_pk_mul_f32 v[6:7], v[32:33], v[24:25]
	s_waitcnt vmcnt(7)
	v_lshlrev_b32_e32 v8, 16, v80
	v_and_b32_e32 v9, 0xffff0000, v80
	v_pk_mul_f32 v[6:7], v[6:7], v[8:9]
	v_pk_mul_f32 v[8:9], v[32:33], v[26:27]
	v_lshlrev_b32_e32 v10, 16, v81
	v_and_b32_e32 v11, 0xffff0000, v81
	v_pk_mul_f32 v[8:9], v[8:9], v[10:11]
	v_cvt_pk_bf16_f32 v6, v6, v7
	v_cvt_pk_bf16_f32 v7, v8, v9
	ds_write_b64 v186, v[6:7] offset:128
	v_pk_mul_f32 v[6:7], v[32:33], v[28:29]
	s_waitcnt vmcnt(7)
	v_lshlrev_b32_e32 v8, 16, v78
	v_and_b32_e32 v9, 0xffff0000, v78
	v_pk_mul_f32 v[6:7], v[6:7], v[8:9]
	v_pk_mul_f32 v[8:9], v[32:33], v[30:31]
	v_lshlrev_b32_e32 v10, 16, v79
	v_and_b32_e32 v11, 0xffff0000, v79
	v_pk_mul_f32 v[8:9], v[8:9], v[10:11]
	v_cvt_pk_bf16_f32 v6, v6, v7
	v_cvt_pk_bf16_f32 v7, v8, v9
	ds_write_b64 v186, v[6:7] offset:160
	v_pk_mul_f32 v[6:7], v[32:33], v[102:103]
	s_waitcnt vmcnt(7)
	v_lshlrev_b32_e32 v8, 16, v76
	v_and_b32_e32 v9, 0xffff0000, v76
	v_pk_mul_f32 v[6:7], v[6:7], v[8:9]
	v_pk_mul_f32 v[8:9], v[32:33], v[104:105]
	v_lshlrev_b32_e32 v10, 16, v77
	v_and_b32_e32 v11, 0xffff0000, v77
	v_pk_mul_f32 v[8:9], v[8:9], v[10:11]
	v_cvt_pk_bf16_f32 v6, v6, v7
	v_cvt_pk_bf16_f32 v7, v8, v9
	ds_write_b64 v186, v[6:7] offset:192
	v_pk_mul_f32 v[0:1], v[32:33], v[0:1]
	s_waitcnt vmcnt(7)
	v_lshlrev_b32_e32 v6, 16, v74
	v_and_b32_e32 v7, 0xffff0000, v74
	v_pk_mul_f32 v[0:1], v[0:1], v[6:7]
	v_pk_mul_f32 v[2:3], v[32:33], v[2:3]
	v_lshlrev_b32_e32 v6, 16, v75
	v_and_b32_e32 v7, 0xffff0000, v75
	v_pk_mul_f32 v[2:3], v[2:3], v[6:7]
	s_add_i32 s22, s22, s94
	s_add_i32 s18, s18, s29
	v_cvt_pk_bf16_f32 v0, v0, v1
	v_cvt_pk_bf16_f32 v1, v2, v3
	s_cmpk_gt_i32 s22, 0x3ff
	ds_write_b64 v186, v[0:1] offset:224
	s_nop 0
	v_readfirstlane_b32 s98, v4
	v_readfirstlane_b32 s99, v5
	s_waitcnt lgkmcnt(0)
	ds_read_b128 v[74:77], v185
	ds_read_b128 v[78:81], v185 offset:1152
	ds_read_b128 v[82:85], v185 offset:2304
	ds_read_b128 v[86:89], v185 offset:3456
	s_waitcnt lgkmcnt(3)
	global_store_dwordx4 v197, v[74:77], s[98:99] offset:2048 nt
	s_waitcnt lgkmcnt(2)
	s_add_u32 s98, s98, s101
	s_addc_u32 s99, s99, 0
	global_store_dwordx4 v197, v[78:81], s[98:99] offset:2048 nt
	s_waitcnt lgkmcnt(1)
	s_add_u32 s98, s98, s101
	s_addc_u32 s99, s99, 0
	global_store_dwordx4 v197, v[82:85], s[98:99] offset:2048 nt
	s_waitcnt lgkmcnt(0)
	s_add_u32 s98, s98, s101
	s_addc_u32 s99, s99, 0
	global_store_dwordx4 v197, v[86:89], s[98:99] offset:2048 nt
	s_cmpk_gt_i32 s22, 0x3ff
	s_barrier
	s_cbranch_scc0 .LBB0_117

.LBB0_125:
	s_and_b32 s10, s2, 0xffffff80
	v_add_u32_e32 v2, s10, v98
	v_mov_b64_e32 v[0:1], s[92:93]
	s_and_b32 s11, s3, 3
	v_mad_i64_i32 v[0:1], s[8:9], v2, s33, v[0:1]
	s_lshl_b32 s8, s11, 9
	s_mov_b32 s9, s96
	v_lshl_add_u64 v[0:1], v[0:1], 0, s[8:9]
	v_lshl_add_u64 v[20:21], v[0:1], 0, v[154:155]
	global_load_dwordx4 v[22:25], v[20:21], off offset:2048
	s_mov_b32 s25, s96
	s_mov_b32 s27, s96
	s_lshl_b32 s24, s11, 15
	s_lshl_b32 s26, s11, 10
	v_add_co_u32_e32 v26, vcc, s35, v20
	v_lshl_add_u64 v[88:89], v[82:83], 0, s[24:25]
	v_lshl_add_u64 v[12:13], v[84:85], 0, s[26:27]
	v_addc_co_u32_e32 v27, vcc, 0, v21, vcc
	global_load_dwordx2 v[4:5], v[88:89], off
	global_load_dwordx2 v[6:7], v[88:89], off offset:32
	global_load_dwordx2 v[0:1], v[88:89], off offset:64
	global_load_dwordx2 v[2:3], v[88:89], off offset:96
	global_load_dwordx4 v[8:11], v[12:13], off offset:16
	s_nop 0
	global_load_dwordx4 v[12:15], v[12:13], off
	s_nop 0
	global_load_dwordx4 v[72:75], v[20:21], off
	global_load_dwordx4 v[16:19], v[26:27], off offset:2304
	global_load_dwordx4 v[56:59], v[26:27], off offset:256
	v_add_co_u32_e32 v28, vcc, s12, v20
	s_mov_b32 s13, 0xf000
	s_nop 0
	v_addc_co_u32_e32 v29, vcc, 0, v21, vcc
	v_add_co_u32_e32 v26, vcc, s13, v20
	global_load_dwordx4 v[76:79], v[28:29], off offset:2560
	global_load_dwordx4 v[44:47], v[28:29], off offset:512
	v_addc_co_u32_e32 v27, vcc, 0, v21, vcc
	global_load_dwordx4 v[68:71], v[26:27], off offset:2816
	global_load_dwordx4 v[32:35], v[26:27], off offset:768
	s_mov_b32 s13, 0x14000
	v_add_co_u32_e32 v28, vcc, s13, v20
	s_mov_b32 s13, 0x19000
	s_nop 0
	v_addc_co_u32_e32 v29, vcc, 0, v21, vcc
	v_add_co_u32_e32 v26, vcc, s13, v20
	s_mov_b32 s13, 0x1e000
	s_waitcnt vmcnt(13)
	v_and_b32_e32 v97, 0xffff0000, v22
	v_lshlrev_b32_e32 v94, 16, v23
	v_lshlrev_b32_e32 v96, 16, v22
	v_mul_f32_e32 v36, v97, v97
	v_and_b32_e32 v95, 0xffff0000, v23
	v_add_f32_e32 v27, 0, v96
	v_mov_b32_e32 v30, v94
	v_mov_b32_e32 v31, v97
	v_pk_fma_f32 v[36:37], v[96:97], v[96:97], v[36:37] op_sel_hi:[1,1,0]
	v_lshlrev_b32_e32 v92, 16, v24
	v_mul_f32_e32 v38, v95, v95
	v_add_f32_e32 v27, v27, v97
	v_pk_fma_f32 v[30:31], v[30:31], v[30:31], v[36:37]
	v_lshlrev_b32_e32 v90, 16, v25
	v_and_b32_e32 v91, 0xffff0000, v25
	v_and_b32_e32 v93, 0xffff0000, v24
	v_mov_b32_e32 v24, v92
	v_mov_b32_e32 v25, v95
	v_add_f32_e32 v27, v27, v94
	v_pk_add_f32 v[30:31], v[38:39], v[30:31] op_sel_hi:[0,1]
	v_mul_f32_e32 v40, v93, v93
	v_add_f32_e32 v27, v27, v95
	v_pk_fma_f32 v[24:25], v[24:25], v[24:25], v[30:31]
	v_mov_b32_e32 v22, v90
	v_mov_b32_e32 v23, v93
	v_add_f32_e32 v27, v27, v92
	v_pk_add_f32 v[24:25], v[40:41], v[24:25] op_sel_hi:[0,1]
	v_add_f32_e32 v27, v27, v93
	v_pk_fma_f32 v[22:23], v[22:23], v[22:23], v[24:25]
	v_mul_f32_e32 v42, v91, v91
	v_add_f32_e32 v43, v27, v90
	v_mov_b32_e32 v23, v91
	v_pk_add_f32 v[22:23], v[42:43], v[22:23]
	ds_bpermute_b32 v25, v100, v23
	ds_bpermute_b32 v24, v100, v22
	v_addc_co_u32_e32 v27, vcc, 0, v21, vcc
	v_add_co_u32_e32 v38, vcc, s13, v20
	s_waitcnt lgkmcnt(0)
	v_pk_add_f32 v[22:23], v[22:23], v[24:25]
	ds_bpermute_b32 v37, v101, v23
	ds_bpermute_b32 v36, v101, v22
	v_addc_co_u32_e32 v39, vcc, 0, v21, vcc
	s_mov_b32 s13, 0x23000
	v_add_co_u32_e32 v20, vcc, s13, v20
	s_waitcnt lgkmcnt(0)
	v_pk_add_f32 v[22:23], v[22:23], v[36:37]
	ds_bpermute_b32 v37, v102, v23
	ds_bpermute_b32 v36, v102, v22
	v_addc_co_u32_e32 v21, vcc, 0, v21, vcc
	global_load_dwordx4 v[60:63], v[28:29], off offset:3072
	s_nop 0
	global_load_dwordx4 v[28:31], v[28:29], off offset:1024
	s_nop 0
	global_load_dwordx4 v[48:51], v[26:27], off offset:3328
	s_nop 0
	global_load_dwordx4 v[24:27], v[26:27], off offset:1280
	s_waitcnt lgkmcnt(0)
	v_pk_add_f32 v[22:23], v[22:23], v[36:37]
	ds_bpermute_b32 v41, v103, v23
	ds_bpermute_b32 v40, v103, v22
	global_load_dwordx4 v[64:67], v[38:39], off offset:3584
	s_nop 0
	global_load_dwordx4 v[36:39], v[38:39], off offset:1536
	s_waitcnt vmcnt(11)
	v_lshlrev_b32_e32 v120, 16, v16
	v_lshlrev_b32_e32 v112, 16, v19
	v_and_b32_e32 v113, 0xffff0000, v19
	s_waitcnt lgkmcnt(0)
	v_pk_add_f32 v[22:23], v[22:23], v[40:41]
	ds_bpermute_b32 v109, v104, v23
	ds_bpermute_b32 v108, v104, v22
	global_load_dwordx4 v[52:55], v[20:21], off offset:3840
	global_load_dwordx4 v[40:43], v[20:21], off offset:1792
	v_and_b32_e32 v121, 0xffff0000, v16
	v_add_f32_e32 v16, 0, v120
	v_lshlrev_b32_e32 v118, 16, v17
	s_waitcnt lgkmcnt(0)
	v_pk_add_f32 v[20:21], v[22:23], v[108:109]
	v_add_f32_e32 v107, v16, v121
	v_pk_mul_f32 v[116:117], v[20:21], s[40:41] op_sel_hi:[1,0]
	v_mul_f32_e32 v22, v121, v121
	v_fma_f32 v19, -v117, v117, v116
	v_max_f32_e32 v19, 0, v19
	v_add_f32_e32 v19, 0x358637bd, v19
	v_and_b32_e32 v119, 0xffff0000, v17
	v_mov_b32_e32 v16, v118
	v_mov_b32_e32 v17, v121
	v_pk_fma_f32 v[22:23], v[120:121], v[120:121], v[22:23] op_sel_hi:[1,1,0]
	v_add_f32_e32 v107, v107, v118
	v_lshlrev_b32_e32 v114, 16, v18
	v_mul_f32_e32 v20, 0x4b800000, v19
	v_cmp_gt_f32_e32 vcc, s19, v19
	v_pk_fma_f32 v[16:17], v[16:17], v[16:17], v[22:23]
	v_add_f32_e32 v23, v107, v119
	v_mul_f32_e32 v22, v119, v119
	v_cndmask_b32_e32 v19, v19, v20, vcc
	v_and_b32_e32 v115, 0xffff0000, v18
	v_mov_b32_e32 v20, v114
	v_mov_b32_e32 v21, v119
	v_pk_add_f32 v[16:17], v[22:23], v[16:17] op_sel_hi:[0,1]
	v_add_f32_e32 v22, v23, v114
	v_pk_fma_f32 v[16:17], v[20:21], v[20:21], v[16:17]
	v_add_f32_e32 v21, v22, v115
	v_mul_f32_e32 v20, v115, v115
	v_rsq_f32_e32 v87, v19
	v_mov_b32_e32 v18, v112
	v_mov_b32_e32 v19, v115
	v_pk_add_f32 v[16:17], v[20:21], v[16:17] op_sel_hi:[0,1]
	v_pk_fma_f32 v[16:17], v[18:19], v[18:19], v[16:17]
	v_add_f32_e32 v21, v21, v112
	v_mul_f32_e32 v20, v113, v113
	v_mov_b32_e32 v17, v113
	v_pk_add_f32 v[108:109], v[20:21], v[16:17]
	ds_bpermute_b32 v111, v100, v109
	ds_bpermute_b32 v110, v100, v108
	global_load_dwordx2 v[20:21], v[88:89], off offset:128
	global_load_dwordx2 v[22:23], v[88:89], off offset:160
	global_load_dwordx2 v[16:17], v[88:89], off offset:192
	global_load_dwordx2 v[18:19], v[88:89], off offset:224
	v_mul_f32_e32 v107, 0x45800000, v87
	v_cndmask_b32_e32 v122, v87, v107, vcc
	v_pk_add_f32 v[96:97], v[96:97], v[116:117] op_sel:[0,1] neg_lo:[0,1] neg_hi:[0,1]
	s_waitcnt lgkmcnt(0)
	v_pk_add_f32 v[88:89], v[108:109], v[110:111]
	ds_bpermute_b32 v109, v101, v89
	ds_bpermute_b32 v108, v101, v88
	v_pk_mul_f32 v[96:97], v[96:97], v[122:123] op_sel_hi:[1,0]
	v_pk_add_f32 v[94:95], v[94:95], v[116:117] op_sel:[0,1] neg_lo:[0,1] neg_hi:[0,1]
	v_pk_mul_f32 v[96:97], v[12:13], v[96:97]
	v_pk_mul_f32 v[94:95], v[94:95], v[122:123] op_sel_hi:[1,0]
	s_waitcnt lgkmcnt(0)
	v_pk_add_f32 v[88:89], v[88:89], v[108:109]
	ds_bpermute_b32 v111, v102, v89
	ds_bpermute_b32 v110, v102, v88
	v_cvt_pk_bf16_f32 v108, v96, v97
	v_pk_mul_f32 v[94:95], v[14:15], v[94:95]
	v_pk_add_f32 v[92:93], v[92:93], v[116:117] op_sel:[0,1] neg_lo:[0,1] neg_hi:[0,1]
	v_cvt_pk_bf16_f32 v109, v94, v95
	s_waitcnt lgkmcnt(0)
	v_pk_add_f32 v[88:89], v[88:89], v[110:111]
	ds_bpermute_b32 v97, v103, v89
	ds_bpermute_b32 v96, v103, v88
	v_pk_add_f32 v[90:91], v[90:91], v[116:117] op_sel:[0,1] neg_lo:[0,1] neg_hi:[0,1]
	v_pk_mul_f32 v[92:93], v[92:93], v[122:123] op_sel_hi:[1,0]
	v_pk_mul_f32 v[90:91], v[90:91], v[122:123] op_sel_hi:[1,0]
	s_waitcnt vmcnt(15)
	v_lshlrev_b32_e32 v122, 16, v76
	s_waitcnt lgkmcnt(0)
	v_pk_add_f32 v[88:89], v[88:89], v[96:97]
	ds_bpermute_b32 v95, v104, v89
	ds_bpermute_b32 v94, v104, v88
	v_and_b32_e32 v123, 0xffff0000, v76
	v_lshlrev_b32_e32 v96, 16, v77
	v_add_f32_e32 v76, 0, v122
	v_mul_f32_e32 v124, v123, v123
	s_waitcnt lgkmcnt(0)
	v_pk_add_f32 v[88:89], v[88:89], v[94:95]
	v_and_b32_e32 v97, 0xffff0000, v77
	v_pk_mul_f32 v[88:89], v[88:89], s[40:41] op_sel_hi:[1,0]
	v_add_f32_e32 v107, v76, v123
	v_fma_f32 v87, -v89, v89, v88
	v_max_f32_e32 v87, 0, v87
	v_mov_b32_e32 v76, v96
	v_mov_b32_e32 v77, v123
	v_pk_fma_f32 v[124:125], v[122:123], v[122:123], v[124:125] op_sel_hi:[1,1,0]
	v_pk_mul_f32 v[92:93], v[8:9], v[92:93]
	v_add_f32_e32 v87, 0x358637bd, v87
	v_lshlrev_b32_e32 v94, 16, v78
	v_pk_fma_f32 v[76:77], v[76:77], v[76:77], v[124:125]
	v_mul_f32_e32 v124, v97, v97
	v_cvt_pk_bf16_f32 v110, v92, v93
	v_mul_f32_e32 v92, 0x4b800000, v87
	v_cmp_gt_f32_e32 vcc, s19, v87
	v_and_b32_e32 v95, 0xffff0000, v78
	v_mov_b32_e32 v116, v94
	v_mov_b32_e32 v117, v97
	v_add_f32_e32 v107, v107, v96
	v_pk_add_f32 v[76:77], v[124:125], v[76:77] op_sel_hi:[0,1]
	v_cndmask_b32_e32 v87, v87, v92, vcc
	v_lshlrev_b32_e32 v92, 16, v79
	v_add_f32_e32 v107, v107, v97
	v_pk_fma_f32 v[76:77], v[116:117], v[116:117], v[76:77]
	v_mul_f32_e32 v116, v95, v95
	v_and_b32_e32 v93, 0xffff0000, v79
	v_mov_b32_e32 v78, v92
	v_mov_b32_e32 v79, v95
	v_add_f32_e32 v107, v107, v94
	v_pk_add_f32 v[76:77], v[116:117], v[76:77] op_sel_hi:[0,1]
	v_add_f32_e32 v107, v107, v95
	v_pk_fma_f32 v[76:77], v[78:79], v[78:79], v[76:77]
	v_add_f32_e32 v117, v107, v92
	v_mul_f32_e32 v116, v93, v93
	v_mov_b32_e32 v77, v93
	v_pk_add_f32 v[76:77], v[116:117], v[76:77]
	ds_bpermute_b32 v79, v100, v77
	ds_bpermute_b32 v78, v100, v76
	v_pk_mul_f32 v[90:91], v[10:11], v[90:91]
	v_rsq_f32_e32 v87, v87
	v_cvt_pk_bf16_f32 v111, v90, v91
	ds_write_b128 v105, v[108:111]
	ds_write_b128 v106, v[72:75]
	s_waitcnt lgkmcnt(2)
	v_pk_add_f32 v[72:73], v[76:77], v[78:79]
	ds_bpermute_b32 v75, v101, v73
	ds_bpermute_b32 v74, v101, v72
	v_mul_f32_e32 v90, 0x45800000, v87
	v_cndmask_b32_e32 v76, v87, v90, vcc
	v_pk_add_f32 v[78:79], v[120:121], v[88:89] op_sel:[0,1] neg_lo:[0,1] neg_hi:[0,1]
	s_waitcnt lgkmcnt(0)
	v_pk_add_f32 v[74:75], v[72:73], v[74:75]
	ds_bpermute_b32 v91, v102, v75
	ds_bpermute_b32 v90, v102, v74
	v_pk_mul_f32 v[78:79], v[78:79], v[76:77] op_sel_hi:[1,0]
	s_waitcnt lgkmcnt(0)
	v_pk_add_f32 v[74:75], v[74:75], v[90:91]
	ds_bpermute_b32 v91, v103, v75
	ds_bpermute_b32 v90, v103, v74
	v_pk_mul_f32 v[78:79], v[12:13], v[78:79]
	s_waitcnt lgkmcnt(0)
	v_pk_add_f32 v[90:91], v[74:75], v[90:91]
	v_cvt_pk_bf16_f32 v72, v78, v79
	v_pk_add_f32 v[78:79], v[118:119], v[88:89] op_sel:[0,1] neg_lo:[0,1] neg_hi:[0,1]
	ds_bpermute_b32 v109, v104, v91
	v_pk_mul_f32 v[78:79], v[78:79], v[76:77] op_sel_hi:[1,0]
	ds_bpermute_b32 v108, v104, v90
	v_pk_mul_f32 v[78:79], v[14:15], v[78:79]
	s_nop 0
	v_cvt_pk_bf16_f32 v73, v78, v79
	v_pk_add_f32 v[78:79], v[114:115], v[88:89] op_sel:[0,1] neg_lo:[0,1] neg_hi:[0,1]
	s_nop 0
	v_pk_mul_f32 v[78:79], v[78:79], v[76:77] op_sel_hi:[1,0]
	s_nop 0
	v_pk_mul_f32 v[78:79], v[8:9], v[78:79]
	s_nop 0
	v_cvt_pk_bf16_f32 v74, v78, v79
	v_pk_add_f32 v[78:79], v[112:113], v[88:89] op_sel:[0,1] neg_lo:[0,1] neg_hi:[0,1]
	s_waitcnt vmcnt(13)
	v_lshlrev_b32_e32 v112, 16, v68
	v_pk_mul_f32 v[76:77], v[78:79], v[76:77] op_sel_hi:[1,0]
	s_waitcnt lgkmcnt(0)
	v_pk_add_f32 v[78:79], v[90:91], v[108:109]
	v_and_b32_e32 v113, 0xffff0000, v68
	v_pk_mul_f32 v[78:79], v[78:79], s[40:41] op_sel_hi:[1,0]
	v_lshlrev_b32_e32 v108, 16, v69
	v_fma_f32 v75, -v79, v79, v78
	v_max_f32_e32 v75, 0, v75
	v_add_f32_e32 v75, 0x358637bd, v75
	v_mul_f32_e32 v87, 0x4b800000, v75
	v_cmp_gt_f32_e32 vcc, s19, v75
	v_add_f32_e32 v68, 0, v112
	v_mul_f32_e32 v114, v113, v113
	v_cndmask_b32_e32 v75, v75, v87, vcc
	v_rsq_f32_e32 v87, v75
	v_and_b32_e32 v109, 0xffff0000, v69
	v_add_f32_e32 v75, v68, v113
	v_mov_b32_e32 v68, v108
	v_mov_b32_e32 v69, v113
	v_pk_fma_f32 v[114:115], v[112:113], v[112:113], v[114:115] op_sel_hi:[1,1,0]
	v_lshlrev_b32_e32 v90, 16, v70
	v_pk_fma_f32 v[68:69], v[68:69], v[68:69], v[114:115]
	v_mul_f32_e32 v114, v109, v109
	v_and_b32_e32 v91, 0xffff0000, v70
	v_mov_b32_e32 v110, v90
	v_mov_b32_e32 v111, v109
	v_add_f32_e32 v75, v75, v108
	v_pk_add_f32 v[68:69], v[114:115], v[68:69] op_sel_hi:[0,1]
	v_lshlrev_b32_e32 v88, 16, v71
	v_add_f32_e32 v75, v75, v109
	v_pk_fma_f32 v[68:69], v[110:111], v[110:111], v[68:69]
	v_mul_f32_e32 v110, v91, v91
	v_and_b32_e32 v89, 0xffff0000, v71
	v_mov_b32_e32 v70, v88
	v_mov_b32_e32 v71, v91
	v_add_f32_e32 v75, v75, v90
	v_pk_add_f32 v[68:69], v[110:111], v[68:69] op_sel_hi:[0,1]
	v_add_f32_e32 v75, v75, v91
	v_pk_fma_f32 v[68:69], v[70:71], v[70:71], v[68:69]
	v_add_f32_e32 v111, v75, v88
	v_mul_f32_e32 v110, v89, v89
	v_mov_b32_e32 v69, v89
	v_pk_add_f32 v[68:69], v[110:111], v[68:69]
	ds_bpermute_b32 v71, v100, v69
	ds_bpermute_b32 v70, v100, v68
	v_pk_mul_f32 v[76:77], v[10:11], v[76:77]
	s_nop 0
	v_cvt_pk_bf16_f32 v75, v76, v77
	ds_write_b128 v105, v[72:75] offset:1088
	ds_write_b128 v106, v[56:59] offset:1088
	s_waitcnt lgkmcnt(2)
	v_pk_add_f32 v[56:57], v[68:69], v[70:71]
	ds_bpermute_b32 v59, v101, v57
	ds_bpermute_b32 v58, v101, v56
	v_mul_f32_e32 v72, 0x45800000, v87
	v_cndmask_b32_e32 v68, v87, v72, vcc
	v_pk_add_f32 v[70:71], v[122:123], v[78:79] op_sel:[0,1] neg_lo:[0,1] neg_hi:[0,1]
	s_waitcnt vmcnt(11)
	v_lshlrev_b32_e32 v76, 16, v61
	s_waitcnt lgkmcnt(0)
	v_pk_add_f32 v[58:59], v[56:57], v[58:59]
	ds_bpermute_b32 v73, v102, v59
	ds_bpermute_b32 v72, v102, v58
	v_pk_mul_f32 v[70:71], v[70:71], v[68:69] op_sel_hi:[1,0]
	v_and_b32_e32 v77, 0xffff0000, v61
	v_pk_mul_f32 v[70:71], v[12:13], v[70:71]
	s_waitcnt lgkmcnt(0)
	v_pk_add_f32 v[58:59], v[58:59], v[72:73]
	ds_bpermute_b32 v73, v103, v59
	ds_bpermute_b32 v72, v103, v58
	v_cvt_pk_bf16_f32 v56, v70, v71
	v_pk_add_f32 v[70:71], v[96:97], v[78:79] op_sel:[0,1] neg_lo:[0,1] neg_hi:[0,1]
	s_waitcnt lgkmcnt(0)
	v_pk_add_f32 v[72:73], v[58:59], v[72:73]
	v_pk_mul_f32 v[70:71], v[70:71], v[68:69] op_sel_hi:[1,0]
	ds_bpermute_b32 v75, v104, v73
	v_pk_mul_f32 v[70:71], v[14:15], v[70:71]
	ds_bpermute_b32 v74, v104, v72
	v_cvt_pk_bf16_f32 v57, v70, v71
	v_pk_add_f32 v[70:71], v[94:95], v[78:79] op_sel:[0,1] neg_lo:[0,1] neg_hi:[0,1]
	s_nop 0
	v_pk_mul_f32 v[70:71], v[70:71], v[68:69] op_sel_hi:[1,0]
	s_nop 0
	v_pk_mul_f32 v[70:71], v[8:9], v[70:71]
	s_nop 0
	v_cvt_pk_bf16_f32 v58, v70, v71
	v_pk_add_f32 v[70:71], v[92:93], v[78:79] op_sel:[0,1] neg_lo:[0,1] neg_hi:[0,1]
	v_and_b32_e32 v93, 0xffff0000, v60
	v_pk_mul_f32 v[68:69], v[70:71], v[68:69] op_sel_hi:[1,0]
	s_waitcnt lgkmcnt(0)
	v_pk_add_f32 v[70:71], v[72:73], v[74:75]
	v_lshlrev_b32_e32 v92, 16, v60
	v_pk_mul_f32 v[70:71], v[70:71], s[40:41] op_sel_hi:[1,0]
	v_mul_f32_e32 v94, v93, v93
	v_fma_f32 v59, -v71, v71, v70
	v_max_f32_e32 v59, 0, v59
	v_add_f32_e32 v59, 0x358637bd, v59
	v_mul_f32_e32 v72, 0x4b800000, v59
	v_cmp_gt_f32_e32 vcc, s19, v59
	v_mov_b32_e32 v60, v76
	v_mov_b32_e32 v61, v93
	v_cndmask_b32_e32 v59, v59, v72, vcc
	v_rsq_f32_e32 v87, v59
	v_add_f32_e32 v59, 0, v92
	v_pk_fma_f32 v[94:95], v[92:93], v[92:93], v[94:95] op_sel_hi:[1,1,0]
	v_lshlrev_b32_e32 v74, 16, v62
	v_add_f32_e32 v59, v59, v93
	v_pk_fma_f32 v[60:61], v[60:61], v[60:61], v[94:95]
	v_mul_f32_e32 v94, v77, v77
	v_and_b32_e32 v75, 0xffff0000, v62
	v_mov_b32_e32 v78, v74
	v_mov_b32_e32 v79, v77
	v_add_f32_e32 v59, v59, v76
	v_pk_add_f32 v[60:61], v[94:95], v[60:61] op_sel_hi:[0,1]
	v_lshlrev_b32_e32 v72, 16, v63
	v_add_f32_e32 v59, v59, v77
	v_pk_fma_f32 v[60:61], v[78:79], v[78:79], v[60:61]
	v_mul_f32_e32 v78, v75, v75
	v_and_b32_e32 v73, 0xffff0000, v63
	v_mov_b32_e32 v62, v72
	v_mov_b32_e32 v63, v75
	v_add_f32_e32 v59, v59, v74
	v_pk_add_f32 v[60:61], v[78:79], v[60:61] op_sel_hi:[0,1]
	v_add_f32_e32 v59, v59, v75
	v_pk_fma_f32 v[60:61], v[62:63], v[62:63], v[60:61]
	v_add_f32_e32 v79, v59, v72
	v_mul_f32_e32 v78, v73, v73
	v_mov_b32_e32 v61, v73
	v_pk_add_f32 v[60:61], v[78:79], v[60:61]
	ds_bpermute_b32 v63, v100, v61
	ds_bpermute_b32 v62, v100, v60
	v_pk_mul_f32 v[68:69], v[10:11], v[68:69]
	s_waitcnt vmcnt(9)
	v_and_b32_e32 v79, 0xffff0000, v48
	v_cvt_pk_bf16_f32 v59, v68, v69
	ds_write_b128 v105, v[56:59] offset:2176
	ds_write_b128 v106, v[44:47] offset:2176
	s_waitcnt lgkmcnt(2)
	v_pk_add_f32 v[44:45], v[60:61], v[62:63]
	ds_bpermute_b32 v47, v101, v45
	ds_bpermute_b32 v46, v101, v44
	v_mul_f32_e32 v56, 0x45800000, v87
	v_cndmask_b32_e32 v56, v87, v56, vcc
	v_pk_add_f32 v[58:59], v[112:113], v[70:71] op_sel:[0,1] neg_lo:[0,1] neg_hi:[0,1]
	v_lshlrev_b32_e32 v68, 16, v49
	s_waitcnt lgkmcnt(0)
	v_pk_add_f32 v[46:47], v[44:45], v[46:47]
	ds_bpermute_b32 v61, v102, v47
	ds_bpermute_b32 v60, v102, v46
	v_pk_mul_f32 v[58:59], v[58:59], v[56:57] op_sel_hi:[1,0]
	v_lshlrev_b32_e32 v78, 16, v48
	v_pk_mul_f32 v[58:59], v[12:13], v[58:59]
	v_and_b32_e32 v69, 0xffff0000, v49
	s_waitcnt lgkmcnt(0)
	v_pk_add_f32 v[46:47], v[46:47], v[60:61]
	ds_bpermute_b32 v61, v103, v47
	ds_bpermute_b32 v60, v103, v46
	v_cvt_pk_bf16_f32 v44, v58, v59
	v_pk_add_f32 v[58:59], v[108:109], v[70:71] op_sel:[0,1] neg_lo:[0,1] neg_hi:[0,1]
	v_mov_b32_e32 v48, v68
	v_pk_mul_f32 v[58:59], v[58:59], v[56:57] op_sel_hi:[1,0]
	s_waitcnt lgkmcnt(0)
	v_pk_add_f32 v[60:61], v[46:47], v[60:61]
	v_pk_mul_f32 v[58:59], v[14:15], v[58:59]
	ds_bpermute_b32 v63, v104, v61
	ds_bpermute_b32 v62, v104, v60
	v_cvt_pk_bf16_f32 v45, v58, v59
	v_pk_add_f32 v[58:59], v[90:91], v[70:71] op_sel:[0,1] neg_lo:[0,1] neg_hi:[0,1]
	v_mov_b32_e32 v49, v79
	v_pk_mul_f32 v[58:59], v[58:59], v[56:57] op_sel_hi:[1,0]
	s_nop 0
	v_pk_mul_f32 v[58:59], v[8:9], v[58:59]
	s_nop 0
	v_cvt_pk_bf16_f32 v46, v58, v59
	v_pk_add_f32 v[58:59], v[88:89], v[70:71] op_sel:[0,1] neg_lo:[0,1] neg_hi:[0,1]
	v_mul_f32_e32 v88, v79, v79
	v_pk_mul_f32 v[56:57], v[58:59], v[56:57] op_sel_hi:[1,0]
	s_waitcnt lgkmcnt(0)
	v_pk_add_f32 v[58:59], v[60:61], v[62:63]
	v_pk_fma_f32 v[88:89], v[78:79], v[78:79], v[88:89] op_sel_hi:[1,1,0]
	v_pk_mul_f32 v[58:59], v[58:59], s[40:41] op_sel_hi:[1,0]
	v_lshlrev_b32_e32 v62, 16, v50
	v_fma_f32 v47, -v59, v59, v58
	v_max_f32_e32 v47, 0, v47
	v_add_f32_e32 v47, 0x358637bd, v47
	v_mul_f32_e32 v60, 0x4b800000, v47
	v_cmp_gt_f32_e32 vcc, s19, v47
	v_pk_fma_f32 v[48:49], v[48:49], v[48:49], v[88:89]
	v_mul_f32_e32 v88, v69, v69
	v_cndmask_b32_e32 v47, v47, v60, vcc
	v_rsq_f32_e32 v87, v47
	v_add_f32_e32 v47, 0, v78
	v_add_f32_e32 v47, v47, v79
	v_and_b32_e32 v63, 0xffff0000, v50
	v_mov_b32_e32 v70, v62
	v_mov_b32_e32 v71, v69
	v_add_f32_e32 v47, v47, v68
	v_pk_add_f32 v[48:49], v[88:89], v[48:49] op_sel_hi:[0,1]
	v_lshlrev_b32_e32 v60, 16, v51
	v_add_f32_e32 v47, v47, v69
	v_pk_fma_f32 v[48:49], v[70:71], v[70:71], v[48:49]
	v_mul_f32_e32 v70, v63, v63
	v_and_b32_e32 v61, 0xffff0000, v51
	v_mov_b32_e32 v50, v60
	v_mov_b32_e32 v51, v63
	v_add_f32_e32 v47, v47, v62
	v_pk_add_f32 v[48:49], v[70:71], v[48:49] op_sel_hi:[0,1]
	v_add_f32_e32 v47, v47, v63
	v_pk_fma_f32 v[48:49], v[50:51], v[50:51], v[48:49]
	v_add_f32_e32 v71, v47, v60
	v_mul_f32_e32 v70, v61, v61
	v_mov_b32_e32 v49, v61
	v_pk_add_f32 v[48:49], v[70:71], v[48:49]
	ds_bpermute_b32 v51, v100, v49
	ds_bpermute_b32 v50, v100, v48
	v_pk_mul_f32 v[56:57], v[10:11], v[56:57]
	s_waitcnt vmcnt(7)
	v_and_b32_e32 v71, 0xffff0000, v64
	v_cvt_pk_bf16_f32 v47, v56, v57
	ds_write_b128 v105, v[44:47] offset:3264
	ds_write_b128 v106, v[32:35] offset:3264
	s_waitcnt lgkmcnt(2)
	v_pk_add_f32 v[32:33], v[48:49], v[50:51]
	ds_bpermute_b32 v35, v101, v33
	ds_bpermute_b32 v34, v101, v32
	v_mul_f32_e32 v44, 0x45800000, v87
	v_cndmask_b32_e32 v44, v87, v44, vcc
	v_pk_add_f32 v[46:47], v[92:93], v[58:59] op_sel:[0,1] neg_lo:[0,1] neg_hi:[0,1]
	v_lshlrev_b32_e32 v70, 16, v64
	s_waitcnt lgkmcnt(0)
	v_pk_add_f32 v[34:35], v[32:33], v[34:35]
	ds_bpermute_b32 v49, v102, v35
	ds_bpermute_b32 v48, v102, v34
	v_pk_mul_f32 v[46:47], v[46:47], v[44:45] op_sel_hi:[1,0]
	s_waitcnt lgkmcnt(0)
	v_pk_add_f32 v[34:35], v[34:35], v[48:49]
	ds_bpermute_b32 v49, v103, v35
	ds_bpermute_b32 v48, v103, v34
	v_pk_mul_f32 v[46:47], v[12:13], v[46:47]
	s_waitcnt lgkmcnt(0)
	v_pk_add_f32 v[48:49], v[34:35], v[48:49]
	v_cvt_pk_bf16_f32 v32, v46, v47
	v_pk_add_f32 v[46:47], v[76:77], v[58:59] op_sel:[0,1] neg_lo:[0,1] neg_hi:[0,1]
	ds_bpermute_b32 v51, v104, v49
	v_pk_mul_f32 v[46:47], v[46:47], v[44:45] op_sel_hi:[1,0]
	ds_bpermute_b32 v50, v104, v48
	v_pk_mul_f32 v[46:47], v[14:15], v[46:47]
	s_nop 0
	v_cvt_pk_bf16_f32 v33, v46, v47
	v_pk_add_f32 v[46:47], v[74:75], v[58:59] op_sel:[0,1] neg_lo:[0,1] neg_hi:[0,1]
	s_nop 0
	v_pk_mul_f32 v[46:47], v[46:47], v[44:45] op_sel_hi:[1,0]
	s_nop 0
	v_pk_mul_f32 v[46:47], v[8:9], v[46:47]
	s_nop 0
	v_cvt_pk_bf16_f32 v34, v46, v47
	v_pk_add_f32 v[46:47], v[72:73], v[58:59] op_sel:[0,1] neg_lo:[0,1] neg_hi:[0,1]
	v_lshlrev_b32_e32 v58, 16, v65
	v_pk_mul_f32 v[44:45], v[46:47], v[44:45] op_sel_hi:[1,0]
	s_waitcnt lgkmcnt(0)
	v_pk_add_f32 v[46:47], v[48:49], v[50:51]
	v_mul_f32_e32 v72, v71, v71
	v_pk_mul_f32 v[46:47], v[46:47], s[40:41] op_sel_hi:[1,0]
	v_and_b32_e32 v59, 0xffff0000, v65
	v_fma_f32 v35, -v47, v47, v46
	v_max_f32_e32 v35, 0, v35
	v_add_f32_e32 v35, 0x358637bd, v35
	v_mul_f32_e32 v48, 0x4b800000, v35
	v_cmp_gt_f32_e32 vcc, s19, v35
	v_mov_b32_e32 v64, v58
	v_mov_b32_e32 v65, v71
	v_cndmask_b32_e32 v35, v35, v48, vcc
	v_rsq_f32_e32 v74, v35
	v_add_f32_e32 v35, 0, v70
	v_pk_fma_f32 v[72:73], v[70:71], v[70:71], v[72:73] op_sel_hi:[1,1,0]
	v_lshlrev_b32_e32 v50, 16, v66
	v_add_f32_e32 v35, v35, v71
	v_pk_fma_f32 v[64:65], v[64:65], v[64:65], v[72:73]
	v_mul_f32_e32 v72, v59, v59
	v_lshlrev_b32_e32 v48, 16, v67
	v_and_b32_e32 v49, 0xffff0000, v67
	v_and_b32_e32 v51, 0xffff0000, v66
	v_mov_b32_e32 v66, v50
	v_mov_b32_e32 v67, v59
	v_add_f32_e32 v35, v35, v58
	v_pk_add_f32 v[64:65], v[72:73], v[64:65] op_sel_hi:[0,1]
	v_add_f32_e32 v35, v35, v59
	v_pk_fma_f32 v[64:65], v[66:67], v[66:67], v[64:65]
	v_mul_f32_e32 v66, v51, v51
	v_mov_b32_e32 v56, v48
	v_mov_b32_e32 v57, v51
	v_add_f32_e32 v35, v35, v50
	v_pk_add_f32 v[64:65], v[66:67], v[64:65] op_sel_hi:[0,1]
	v_add_f32_e32 v35, v35, v51
	v_pk_fma_f32 v[56:57], v[56:57], v[56:57], v[64:65]
	v_add_f32_e32 v67, v35, v48
	v_mul_f32_e32 v66, v49, v49
	v_mov_b32_e32 v57, v49
	v_pk_add_f32 v[56:57], v[66:67], v[56:57]
	ds_bpermute_b32 v65, v100, v57
	ds_bpermute_b32 v64, v100, v56
	v_pk_mul_f32 v[44:45], v[10:11], v[44:45]
	s_nop 0
	v_cvt_pk_bf16_f32 v35, v44, v45
	ds_write_b128 v105, v[32:35] offset:4352
	ds_write_b128 v106, v[28:31] offset:4352
	s_waitcnt lgkmcnt(2)
	v_pk_add_f32 v[28:29], v[56:57], v[64:65]
	ds_bpermute_b32 v31, v101, v29
	ds_bpermute_b32 v30, v101, v28
	v_mul_f32_e32 v32, 0x45800000, v74
	v_cndmask_b32_e32 v32, v74, v32, vcc
	v_pk_add_f32 v[34:35], v[78:79], v[46:47] op_sel:[0,1] neg_lo:[0,1] neg_hi:[0,1]
	s_waitcnt lgkmcnt(0)
	v_pk_add_f32 v[30:31], v[28:29], v[30:31]
	ds_bpermute_b32 v45, v102, v31
	ds_bpermute_b32 v44, v102, v30
	v_pk_mul_f32 v[34:35], v[34:35], v[32:33] op_sel_hi:[1,0]
	s_waitcnt lgkmcnt(0)
	v_pk_add_f32 v[30:31], v[30:31], v[44:45]
	ds_bpermute_b32 v45, v103, v31
	ds_bpermute_b32 v44, v103, v30
	v_pk_mul_f32 v[34:35], v[12:13], v[34:35]
	s_waitcnt lgkmcnt(0)
	v_pk_add_f32 v[44:45], v[30:31], v[44:45]
	v_cvt_pk_bf16_f32 v28, v34, v35
	v_pk_add_f32 v[34:35], v[68:69], v[46:47] op_sel:[0,1] neg_lo:[0,1] neg_hi:[0,1]
	ds_bpermute_b32 v57, v104, v45
	v_pk_mul_f32 v[34:35], v[34:35], v[32:33] op_sel_hi:[1,0]
	ds_bpermute_b32 v56, v104, v44
	v_pk_mul_f32 v[34:35], v[14:15], v[34:35]
	s_nop 0
	v_cvt_pk_bf16_f32 v29, v34, v35
	v_pk_add_f32 v[34:35], v[62:63], v[46:47] op_sel:[0,1] neg_lo:[0,1] neg_hi:[0,1]
	s_waitcnt vmcnt(5)
	v_and_b32_e32 v63, 0xffff0000, v52
	v_pk_mul_f32 v[34:35], v[34:35], v[32:33] op_sel_hi:[1,0]
	v_lshlrev_b32_e32 v62, 16, v52
	v_pk_mul_f32 v[34:35], v[8:9], v[34:35]
	v_mul_f32_e32 v64, v63, v63
	v_cvt_pk_bf16_f32 v30, v34, v35
	v_pk_add_f32 v[34:35], v[60:61], v[46:47] op_sel:[0,1] neg_lo:[0,1] neg_hi:[0,1]
	v_pk_fma_f32 v[64:65], v[62:63], v[62:63], v[64:65] op_sel_hi:[1,1,0]
	v_pk_mul_f32 v[32:33], v[34:35], v[32:33] op_sel_hi:[1,0]
	s_waitcnt lgkmcnt(0)
	v_pk_add_f32 v[34:35], v[44:45], v[56:57]
	v_lshlrev_b32_e32 v56, 16, v53
	v_pk_mul_f32 v[34:35], v[34:35], s[40:41] op_sel_hi:[1,0]
	v_and_b32_e32 v57, 0xffff0000, v53
	v_fma_f32 v31, -v35, v35, v34
	v_max_f32_e32 v31, 0, v31
	v_add_f32_e32 v31, 0x358637bd, v31
	v_mul_f32_e32 v44, 0x4b800000, v31
	v_cmp_gt_f32_e32 vcc, s19, v31
	v_mov_b32_e32 v52, v56
	v_mov_b32_e32 v53, v63
	v_cndmask_b32_e32 v31, v31, v44, vcc
	v_rsq_f32_e32 v66, v31
	v_add_f32_e32 v31, 0, v62
	v_lshlrev_b32_e32 v46, 16, v54
	v_add_f32_e32 v31, v31, v63
	v_pk_fma_f32 v[52:53], v[52:53], v[52:53], v[64:65]
	v_mul_f32_e32 v64, v57, v57
	v_and_b32_e32 v47, 0xffff0000, v54
	v_mov_b32_e32 v60, v46
	v_mov_b32_e32 v61, v57
	v_add_f32_e32 v31, v31, v56
	v_pk_add_f32 v[52:53], v[64:65], v[52:53] op_sel_hi:[0,1]
	v_lshlrev_b32_e32 v44, 16, v55
	v_add_f32_e32 v31, v31, v57
	v_pk_fma_f32 v[52:53], v[60:61], v[60:61], v[52:53]
	v_mul_f32_e32 v60, v47, v47
	v_and_b32_e32 v45, 0xffff0000, v55
	v_mov_b32_e32 v54, v44
	v_mov_b32_e32 v55, v47
	v_add_f32_e32 v31, v31, v46
	v_pk_add_f32 v[52:53], v[60:61], v[52:53] op_sel_hi:[0,1]
	v_add_f32_e32 v31, v31, v47
	v_pk_fma_f32 v[52:53], v[54:55], v[54:55], v[52:53]
	v_add_f32_e32 v61, v31, v44
	v_mul_f32_e32 v60, v45, v45
	v_mov_b32_e32 v53, v45
	v_pk_add_f32 v[52:53], v[60:61], v[52:53]
	ds_bpermute_b32 v55, v100, v53
	ds_bpermute_b32 v54, v100, v52
	v_pk_mul_f32 v[32:33], v[10:11], v[32:33]
	s_nop 0
	v_cvt_pk_bf16_f32 v31, v32, v33
	ds_write_b128 v105, v[28:31] offset:5440
	ds_write_b128 v106, v[24:27] offset:5440
	s_waitcnt lgkmcnt(2)
	v_pk_add_f32 v[24:25], v[52:53], v[54:55]
	ds_bpermute_b32 v27, v101, v25
	ds_bpermute_b32 v26, v101, v24
	v_mul_f32_e32 v28, 0x45800000, v66
	v_cndmask_b32_e32 v28, v66, v28, vcc
	v_pk_add_f32 v[30:31], v[70:71], v[34:35] op_sel:[0,1] neg_lo:[0,1] neg_hi:[0,1]
	s_waitcnt lgkmcnt(0)
	v_pk_add_f32 v[26:27], v[24:25], v[26:27]
	ds_bpermute_b32 v33, v102, v27
	ds_bpermute_b32 v32, v102, v26
	v_pk_mul_f32 v[30:31], v[30:31], v[28:29] op_sel_hi:[1,0]
	s_waitcnt lgkmcnt(0)
	v_pk_add_f32 v[26:27], v[26:27], v[32:33]
	ds_bpermute_b32 v33, v103, v27
	ds_bpermute_b32 v32, v103, v26
	v_pk_mul_f32 v[30:31], v[12:13], v[30:31]
	s_waitcnt lgkmcnt(0)
	v_pk_add_f32 v[32:33], v[26:27], v[32:33]
	v_cvt_pk_bf16_f32 v24, v30, v31
	v_pk_add_f32 v[30:31], v[58:59], v[34:35] op_sel:[0,1] neg_lo:[0,1] neg_hi:[0,1]
	s_nop 0
	v_pk_mul_f32 v[30:31], v[30:31], v[28:29] op_sel_hi:[1,0]
	s_nop 0
	v_pk_mul_f32 v[30:31], v[14:15], v[30:31]
	s_nop 0
	v_cvt_pk_bf16_f32 v25, v30, v31
	v_pk_add_f32 v[30:31], v[50:51], v[34:35] op_sel:[0,1] neg_lo:[0,1] neg_hi:[0,1]
	ds_bpermute_b32 v51, v104, v33
	ds_bpermute_b32 v50, v104, v32
	v_pk_mul_f32 v[30:31], v[30:31], v[28:29] op_sel_hi:[1,0]
	s_nop 0
	v_pk_mul_f32 v[30:31], v[8:9], v[30:31]
	s_nop 0
	v_cvt_pk_bf16_f32 v26, v30, v31
	v_pk_add_f32 v[30:31], v[48:49], v[34:35] op_sel:[0,1] neg_lo:[0,1] neg_hi:[0,1]
	s_nop 0
	v_pk_mul_f32 v[28:29], v[30:31], v[28:29] op_sel_hi:[1,0]
	s_waitcnt lgkmcnt(0)
	v_pk_add_f32 v[30:31], v[32:33], v[50:51]
	v_pk_mul_f32 v[28:29], v[10:11], v[28:29]
	v_pk_mul_f32 v[30:31], v[30:31], s[40:41] op_sel_hi:[1,0]
	s_nop 0
	v_fma_f32 v27, -v31, v31, v30
	v_max_f32_e32 v27, 0, v27
	v_add_f32_e32 v27, 0x358637bd, v27
	v_mul_f32_e32 v32, 0x4b800000, v27
	v_cmp_gt_f32_e32 vcc, s19, v27
	s_nop 1
	v_cndmask_b32_e32 v27, v27, v32, vcc
	v_rsq_f32_e32 v32, v27
	v_cvt_pk_bf16_f32 v27, v28, v29
	ds_write_b128 v105, v[24:27] offset:6528
	ds_write_b128 v106, v[36:39] offset:6528
	v_pk_add_f32 v[26:27], v[62:63], v[30:31] op_sel:[0,1] neg_lo:[0,1] neg_hi:[0,1]
	v_mul_f32_e32 v24, 0x45800000, v32
	v_cndmask_b32_e32 v24, v32, v24, vcc
	v_pk_mul_f32 v[26:27], v[26:27], v[24:25] op_sel_hi:[1,0]
	s_nop 0
	v_pk_mul_f32 v[12:13], v[12:13], v[26:27]
	v_pk_add_f32 v[26:27], v[56:57], v[30:31] op_sel:[0,1] neg_lo:[0,1] neg_hi:[0,1]
	v_cvt_pk_bf16_f32 v12, v12, v13
	v_pk_mul_f32 v[26:27], v[26:27], v[24:25] op_sel_hi:[1,0]
	s_nop 0
	v_pk_mul_f32 v[14:15], v[14:15], v[26:27]
	s_nop 0
	v_cvt_pk_bf16_f32 v13, v14, v15
	v_pk_add_f32 v[14:15], v[46:47], v[30:31] op_sel:[0,1] neg_lo:[0,1] neg_hi:[0,1]
	s_nop 0
	v_pk_mul_f32 v[14:15], v[14:15], v[24:25] op_sel_hi:[1,0]
	s_nop 0
	v_pk_mul_f32 v[8:9], v[8:9], v[14:15]
	s_nop 0
	v_cvt_pk_bf16_f32 v14, v8, v9
	v_pk_add_f32 v[8:9], v[44:45], v[30:31] op_sel:[0,1] neg_lo:[0,1] neg_hi:[0,1]
	s_nop 0
	v_pk_mul_f32 v[8:9], v[8:9], v[24:25] op_sel_hi:[1,0]
	s_nop 0
	v_pk_mul_f32 v[8:9], v[10:11], v[8:9]
	s_nop 0
	v_cvt_pk_bf16_f32 v15, v8, v9
	v_lshl_add_u32 v8, s11, 7, v80
	v_ashrrev_i32_e32 v9, 31, v8
	v_lshl_add_u64 v[8:9], v[8:9], 2, s[54:55]
	ds_write_b128 v105, v[12:15] offset:7616
	s_waitcnt vmcnt(4)
	ds_write_b128 v106, v[40:43] offset:7616
	s_waitcnt lgkmcnt(0)
	s_barrier
	global_load_dword v28, v[8:9], off
	ds_read_b64_tr_b16 v[8:9], v99
	ds_read_b64_tr_b16 v[12:13], v99 offset:32
	ds_read_b64_tr_b16 v[24:25], v99 offset:64
	ds_read_b64_tr_b16 v[30:31], v99 offset:96
	ds_read_b64_tr_b16 v[10:11], v99 offset:8704
	ds_read_b64_tr_b16 v[14:15], v99 offset:8736
	ds_read_b64_tr_b16 v[26:27], v99 offset:8768
	ds_read_b64_tr_b16 v[32:33], v99 offset:8800
	ds_read_b64_tr_b16 v[34:35], v99 offset:128
	ds_read_b64_tr_b16 v[38:39], v99 offset:160
	ds_read_b64_tr_b16 v[42:43], v99 offset:192
	ds_read_b64_tr_b16 v[46:47], v99 offset:224
	ds_read_b64_tr_b16 v[36:37], v99 offset:8832
	ds_read_b64_tr_b16 v[40:41], v99 offset:8864
	ds_read_b64_tr_b16 v[44:45], v99 offset:8896
	ds_read_b64_tr_b16 v[48:49], v99 offset:8928
	ds_read_b64_tr_b16 v[50:51], v99 offset:256
	ds_read_b64_tr_b16 v[54:55], v99 offset:288
	ds_read_b64_tr_b16 v[58:59], v99 offset:320
	ds_read_b64_tr_b16 v[62:63], v99 offset:352
	ds_read_b64_tr_b16 v[52:53], v99 offset:8960
	ds_read_b64_tr_b16 v[56:57], v99 offset:8992
	ds_read_b64_tr_b16 v[60:61], v99 offset:9024
	ds_read_b64_tr_b16 v[64:65], v99 offset:9056
	ds_read_b64_tr_b16 v[66:67], v99 offset:384
	ds_read_b64_tr_b16 v[70:71], v99 offset:416
	ds_read_b64_tr_b16 v[74:75], v99 offset:448
	ds_read_b64_tr_b16 v[88:89], v99 offset:480
	ds_read_b64_tr_b16 v[68:69], v99 offset:9088
	ds_read_b64_tr_b16 v[72:73], v99 offset:9120
	ds_read_b64_tr_b16 v[76:77], v99 offset:9152
	ds_read_b64_tr_b16 v[90:91], v99 offset:9184
	ds_read_b64_tr_b16 v[92:93], v99 offset:17408
	ds_read_b64_tr_b16 v[108:109], v99 offset:17440
	ds_read_b64_tr_b16 v[112:113], v99 offset:17472
	ds_read_b64_tr_b16 v[116:117], v99 offset:17504
	ds_read_b64_tr_b16 v[94:95], v99 offset:26112
	ds_read_b64_tr_b16 v[110:111], v99 offset:26144
	ds_read_b64_tr_b16 v[114:115], v99 offset:26176
	ds_read_b64_tr_b16 v[118:119], v99 offset:26208
	ds_read_b64_tr_b16 v[120:121], v99 offset:17536
	ds_read_b64_tr_b16 v[124:125], v99 offset:17568
	ds_read_b64_tr_b16 v[128:129], v99 offset:17600
	ds_read_b64_tr_b16 v[132:133], v99 offset:17632
	ds_read_b64_tr_b16 v[122:123], v99 offset:26240
	ds_read_b64_tr_b16 v[126:127], v99 offset:26272
	ds_read_b64_tr_b16 v[130:131], v99 offset:26304
	ds_read_b64_tr_b16 v[134:135], v99 offset:26336
	ds_read_b64_tr_b16 v[136:137], v99 offset:17664
	ds_read_b64_tr_b16 v[140:141], v99 offset:17696
	ds_read_b64_tr_b16 v[144:145], v99 offset:17728
	ds_read_b64_tr_b16 v[148:149], v99 offset:17760
	ds_read_b64_tr_b16 v[138:139], v99 offset:26368
	ds_read_b64_tr_b16 v[142:143], v99 offset:26400
	ds_read_b64_tr_b16 v[146:147], v99 offset:26432
	ds_read_b64_tr_b16 v[150:151], v99 offset:26464
	ds_read_b64_tr_b16 v[156:157], v99 offset:17792
	ds_read_b64_tr_b16 v[160:161], v99 offset:17824
	ds_read_b64_tr_b16 v[164:165], v99 offset:17856
	ds_read_b64_tr_b16 v[168:169], v99 offset:17888
	ds_read_b64_tr_b16 v[158:159], v99 offset:26496
	ds_read_b64_tr_b16 v[162:163], v99 offset:26528
	ds_read_b64_tr_b16 v[166:167], v99 offset:26560
	ds_read_b64_tr_b16 v[170:171], v99 offset:26592
	s_waitcnt lgkmcnt(14)
	v_mfma_f32_16x16x32_bf16 v[8:11], v[8:11], v[4:7], 0
	v_mfma_f32_16x16x32_bf16 v[12:15], v[12:15], v[4:7], 0
	v_mfma_f32_16x16x32_bf16 v[24:27], v[24:27], v[4:7], 0
	v_mfma_f32_16x16x32_bf16 v[30:33], v[30:33], v[4:7], 0
	v_mfma_f32_16x16x32_bf16 v[34:37], v[34:37], v[4:7], 0
	v_mfma_f32_16x16x32_bf16 v[38:41], v[38:41], v[4:7], 0
	v_mfma_f32_16x16x32_bf16 v[42:45], v[42:45], v[4:7], 0
	v_mfma_f32_16x16x32_bf16 v[46:49], v[46:49], v[4:7], 0
	v_mfma_f32_16x16x32_bf16 v[50:53], v[50:53], v[4:7], 0
	v_mfma_f32_16x16x32_bf16 v[54:57], v[54:57], v[4:7], 0
	v_mfma_f32_16x16x32_bf16 v[58:61], v[58:61], v[4:7], 0
	v_mfma_f32_16x16x32_bf16 v[62:65], v[62:65], v[4:7], 0
	v_mfma_f32_16x16x32_bf16 v[66:69], v[66:69], v[4:7], 0
	v_mfma_f32_16x16x32_bf16 v[70:73], v[70:73], v[4:7], 0
	v_mfma_f32_16x16x32_bf16 v[74:77], v[74:77], v[4:7], 0
	v_mfma_f32_16x16x32_bf16 v[4:7], v[88:91], v[4:7], 0
	ds_read_b64_tr_b16 v[88:89], v99 offset:34816
	ds_read_b64_tr_b16 v[172:173], v99 offset:34848
	ds_read_b64_tr_b16 v[178:179], v99 offset:34880
	ds_read_b64_tr_b16 v[182:183], v99 offset:34912
	ds_read_b64_tr_b16 v[90:91], v99 offset:43520
	ds_read_b64_tr_b16 v[174:175], v99 offset:43552
	ds_read_b64_tr_b16 v[180:181], v99 offset:43584
	ds_read_b64_tr_b16 v[184:185], v99 offset:43616
	ds_read_b64_tr_b16 v[188:189], v99 offset:34944
	ds_read_b64_tr_b16 v[192:193], v99 offset:34976
	ds_read_b64_tr_b16 v[202:203], v99 offset:35008
	ds_read_b64_tr_b16 v[206:207], v99 offset:35040
	ds_read_b64_tr_b16 v[190:191], v99 offset:43648
	ds_read_b64_tr_b16 v[194:195], v99 offset:43680
	ds_read_b64_tr_b16 v[204:205], v99 offset:43712
	ds_read_b64_tr_b16 v[208:209], v99 offset:43744
	ds_read_b64_tr_b16 v[210:211], v99 offset:35072
	ds_read_b64_tr_b16 v[214:215], v99 offset:35104
	ds_read_b64_tr_b16 v[218:219], v99 offset:35136
	ds_read_b64_tr_b16 v[222:223], v99 offset:35168
	ds_read_b64_tr_b16 v[212:213], v99 offset:43776
	ds_read_b64_tr_b16 v[216:217], v99 offset:43808
	ds_read_b64_tr_b16 v[220:221], v99 offset:43840
	ds_read_b64_tr_b16 v[224:225], v99 offset:43872
	ds_read_b64_tr_b16 v[226:227], v99 offset:35200
	ds_read_b64_tr_b16 v[230:231], v99 offset:35232
	ds_read_b64_tr_b16 v[234:235], v99 offset:35264
	ds_read_b64_tr_b16 v[238:239], v99 offset:35296
	ds_read_b64_tr_b16 v[228:229], v99 offset:43904
	ds_read_b64_tr_b16 v[232:233], v99 offset:43936
	ds_read_b64_tr_b16 v[236:237], v99 offset:43968
	ds_read_b64_tr_b16 v[240:241], v99 offset:44000
	v_mfma_f32_16x16x32_bf16 v[8:11], v[92:95], v[0:3], v[8:11]
	v_mfma_f32_16x16x32_bf16 v[12:15], v[108:111], v[0:3], v[12:15]
	v_mfma_f32_16x16x32_bf16 v[24:27], v[112:115], v[0:3], v[24:27]
	v_mfma_f32_16x16x32_bf16 v[30:33], v[116:119], v[0:3], v[30:33]
	v_mfma_f32_16x16x32_bf16 v[34:37], v[120:123], v[0:3], v[34:37]
	v_mfma_f32_16x16x32_bf16 v[38:41], v[124:127], v[0:3], v[38:41]
	v_mfma_f32_16x16x32_bf16 v[42:45], v[128:131], v[0:3], v[42:45]
	v_mfma_f32_16x16x32_bf16 v[46:49], v[132:135], v[0:3], v[46:49]
	s_waitcnt lgkmcnt(14)
	v_mfma_f32_16x16x32_bf16 v[50:53], v[136:139], v[0:3], v[50:53]
	v_mfma_f32_16x16x32_bf16 v[54:57], v[140:143], v[0:3], v[54:57]
	v_mfma_f32_16x16x32_bf16 v[58:61], v[144:147], v[0:3], v[58:61]
	v_mfma_f32_16x16x32_bf16 v[62:65], v[148:151], v[0:3], v[62:65]
	v_mfma_f32_16x16x32_bf16 v[66:69], v[156:159], v[0:3], v[66:69]
	v_mfma_f32_16x16x32_bf16 v[70:73], v[160:163], v[0:3], v[70:73]
	v_mfma_f32_16x16x32_bf16 v[74:77], v[164:167], v[0:3], v[74:77]
	v_mfma_f32_16x16x32_bf16 v[0:3], v[168:171], v[0:3], v[4:7]
	s_nop 2
	ds_read_b64_tr_b16 v[4:5], v99 offset:52224
	ds_read_b64_tr_b16 v[92:93], v99 offset:52256
	ds_read_b64_tr_b16 v[108:109], v99 offset:52288
	ds_read_b64_tr_b16 v[112:113], v99 offset:52320
	ds_read_b64_tr_b16 v[6:7], v99 offset:60928
	ds_read_b64_tr_b16 v[94:95], v99 offset:60960
	ds_read_b64_tr_b16 v[110:111], v99 offset:60992
	ds_read_b64_tr_b16 v[114:115], v99 offset:61024
	ds_read_b64_tr_b16 v[116:117], v99 offset:52352
	ds_read_b64_tr_b16 v[120:121], v99 offset:52384
	ds_read_b64_tr_b16 v[124:125], v99 offset:52416
	ds_read_b64_tr_b16 v[128:129], v99 offset:52448
	ds_read_b64_tr_b16 v[118:119], v99 offset:61056
	ds_read_b64_tr_b16 v[122:123], v99 offset:61088
	ds_read_b64_tr_b16 v[126:127], v99 offset:61120
	ds_read_b64_tr_b16 v[130:131], v99 offset:61152
	ds_read_b64_tr_b16 v[132:133], v99 offset:52480
	ds_read_b64_tr_b16 v[136:137], v99 offset:52512
	ds_read_b64_tr_b16 v[140:141], v99 offset:52544
	ds_read_b64_tr_b16 v[144:145], v99 offset:52576
	ds_read_b64_tr_b16 v[134:135], v99 offset:61184
	ds_read_b64_tr_b16 v[138:139], v99 offset:61216
	ds_read_b64_tr_b16 v[142:143], v99 offset:61248
	ds_read_b64_tr_b16 v[146:147], v99 offset:61280
	ds_read_b64_tr_b16 v[148:149], v99 offset:52608
	ds_read_b64_tr_b16 v[156:157], v99 offset:52640
	ds_read_b64_tr_b16 v[160:161], v99 offset:52672
	ds_read_b64_tr_b16 v[164:165], v99 offset:52704
	ds_read_b64_tr_b16 v[150:151], v99 offset:61312
	ds_read_b64_tr_b16 v[158:159], v99 offset:61344
	ds_read_b64_tr_b16 v[162:163], v99 offset:61376
	ds_read_b64_tr_b16 v[166:167], v99 offset:61408
	s_waitcnt vmcnt(3)
	v_mfma_f32_16x16x32_bf16 v[8:11], v[88:91], v[20:23], v[8:11]
	v_mfma_f32_16x16x32_bf16 v[12:15], v[172:175], v[20:23], v[12:15]
	v_mfma_f32_16x16x32_bf16 v[24:27], v[178:181], v[20:23], v[24:27]
	v_mfma_f32_16x16x32_bf16 v[30:33], v[182:185], v[20:23], v[30:33]
	v_mfma_f32_16x16x32_bf16 v[34:37], v[188:191], v[20:23], v[34:37]
	v_mfma_f32_16x16x32_bf16 v[38:41], v[192:195], v[20:23], v[38:41]
	v_mfma_f32_16x16x32_bf16 v[42:45], v[202:205], v[20:23], v[42:45]
	v_mfma_f32_16x16x32_bf16 v[46:49], v[206:209], v[20:23], v[46:49]
	s_waitcnt lgkmcnt(14)
	v_mfma_f32_16x16x32_bf16 v[50:53], v[210:213], v[20:23], v[50:53]
	v_mfma_f32_16x16x32_bf16 v[54:57], v[214:217], v[20:23], v[54:57]
	v_mfma_f32_16x16x32_bf16 v[58:61], v[218:221], v[20:23], v[58:61]
	v_mfma_f32_16x16x32_bf16 v[62:65], v[222:225], v[20:23], v[62:65]
	v_mfma_f32_16x16x32_bf16 v[66:69], v[226:229], v[20:23], v[66:69]
	v_mfma_f32_16x16x32_bf16 v[70:73], v[230:233], v[20:23], v[70:73]
	v_mfma_f32_16x16x32_bf16 v[74:77], v[234:237], v[20:23], v[74:77]
	v_mfma_f32_16x16x32_bf16 v[0:3], v[238:241], v[20:23], v[0:3]
	s_waitcnt vmcnt(1)
	v_mfma_f32_16x16x32_bf16 v[88:91], v[4:7], v[16:19], v[8:11]
	v_mfma_f32_16x16x32_bf16 v[92:95], v[92:95], v[16:19], v[12:15]
	v_mfma_f32_16x16x32_bf16 v[108:111], v[108:111], v[16:19], v[24:27]
	v_mfma_f32_16x16x32_bf16 v[30:33], v[112:115], v[16:19], v[30:33]
	v_mfma_f32_16x16x32_bf16 v[34:37], v[116:119], v[16:19], v[34:37]
	v_mfma_f32_16x16x32_bf16 v[38:41], v[120:123], v[16:19], v[38:41]
	v_mfma_f32_16x16x32_bf16 v[42:45], v[124:127], v[16:19], v[42:45]
	v_mfma_f32_16x16x32_bf16 v[46:49], v[128:131], v[16:19], v[46:49]
	s_waitcnt lgkmcnt(11)
	v_mfma_f32_16x16x32_bf16 v[50:53], v[132:135], v[16:19], v[50:53]
	s_waitcnt lgkmcnt(10)
	v_mfma_f32_16x16x32_bf16 v[54:57], v[136:139], v[16:19], v[54:57]
	s_waitcnt lgkmcnt(9)
	v_mfma_f32_16x16x32_bf16 v[24:27], v[140:143], v[16:19], v[58:61]
	s_waitcnt lgkmcnt(8)
	v_mfma_f32_16x16x32_bf16 v[20:23], v[144:147], v[16:19], v[62:65]
	s_waitcnt lgkmcnt(3)
	v_mfma_f32_16x16x32_bf16 v[12:15], v[148:151], v[16:19], v[66:69]
	s_waitcnt lgkmcnt(2)
	v_mfma_f32_16x16x32_bf16 v[8:11], v[156:159], v[16:19], v[70:73]
	s_waitcnt lgkmcnt(1)
	v_mfma_f32_16x16x32_bf16 v[4:7], v[160:163], v[16:19], v[74:77]
	s_waitcnt lgkmcnt(0)
	v_mfma_f32_16x16x32_bf16 v[0:3], v[164:167], v[16:19], v[0:3]
	ds_read2_b64 v[58:61], v81 offset1:4
	v_add_u32_e32 v18, s10, v80
	v_mov_b64_e32 v[16:17], s[38:39]
	v_mad_i64_i32 v[16:17], s[10:11], v18, s34, v[16:17]
	s_waitcnt lgkmcnt(0)
	v_lshlrev_b32_e32 v18, 16, v58
	v_and_b32_e32 v19, 0xffff0000, v58
	s_waitcnt vmcnt(0)
	v_pk_add_f32 v[62:63], v[28:29], v[88:89] op_sel_hi:[0,1]
	v_pk_mul_f32 v[18:19], v[62:63], v[18:19]
	v_lshlrev_b32_e32 v58, 16, v59
	v_and_b32_e32 v59, 0xffff0000, v59
	v_pk_add_f32 v[62:63], v[28:29], v[90:91] op_sel_hi:[0,1]
	v_lshl_add_u64 v[16:17], v[16:17], 0, s[8:9]
	v_mov_b32_e32 v87, v155
	v_pk_mul_f32 v[58:59], v[62:63], v[58:59]
	v_lshl_add_u64 v[16:17], v[16:17], 0, v[86:87]
	v_cvt_pk_bf16_f32 v18, v18, v19
	v_cvt_pk_bf16_f32 v19, v58, v59
	ds_write_b64 v81, v[18:19]
	v_lshlrev_b32_e32 v18, 16, v60
	v_and_b32_e32 v19, 0xffff0000, v60
	v_pk_add_f32 v[58:59], v[28:29], v[92:93] op_sel_hi:[0,1]
	v_pk_mul_f32 v[18:19], v[58:59], v[18:19]
	v_lshlrev_b32_e32 v62, 16, v61
	v_and_b32_e32 v63, 0xffff0000, v61
	ds_read2_b64 v[58:61], v81 offset0:8 offset1:12
	v_pk_add_f32 v[64:65], v[28:29], v[94:95] op_sel_hi:[0,1]
	v_pk_mul_f32 v[62:63], v[64:65], v[62:63]
	v_cvt_pk_bf16_f32 v18, v18, v19
	v_cvt_pk_bf16_f32 v19, v62, v63
	ds_write_b64 v81, v[18:19] offset:32
	s_waitcnt lgkmcnt(0)
	v_lshlrev_b32_e32 v18, 16, v58
	v_and_b32_e32 v19, 0xffff0000, v58
	v_pk_add_f32 v[62:63], v[28:29], v[108:109] op_sel_hi:[0,1]
	v_pk_mul_f32 v[18:19], v[62:63], v[18:19]
	v_lshlrev_b32_e32 v58, 16, v59
	v_and_b32_e32 v59, 0xffff0000, v59
	v_pk_add_f32 v[62:63], v[28:29], v[110:111] op_sel_hi:[0,1]
	v_pk_mul_f32 v[58:59], v[62:63], v[58:59]
	v_cvt_pk_bf16_f32 v18, v18, v19
	v_cvt_pk_bf16_f32 v19, v58, v59
	ds_write_b64 v81, v[18:19] offset:64
	v_lshlrev_b32_e32 v18, 16, v60
	v_and_b32_e32 v19, 0xffff0000, v60
	v_pk_add_f32 v[30:31], v[28:29], v[30:31] op_sel_hi:[0,1]
	v_pk_mul_f32 v[18:19], v[30:31], v[18:19]
	v_lshlrev_b32_e32 v30, 16, v61
	v_and_b32_e32 v31, 0xffff0000, v61
	ds_read2_b64 v[58:61], v81 offset0:16 offset1:20
	v_pk_add_f32 v[32:33], v[28:29], v[32:33] op_sel_hi:[0,1]
	v_pk_mul_f32 v[30:31], v[32:33], v[30:31]
	v_cvt_pk_bf16_f32 v18, v18, v19
	v_cvt_pk_bf16_f32 v19, v30, v31
	ds_write_b64 v81, v[18:19] offset:96
	s_waitcnt lgkmcnt(0)
	v_lshlrev_b32_e32 v18, 16, v58
	v_and_b32_e32 v19, 0xffff0000, v58
	v_pk_add_f32 v[30:31], v[28:29], v[34:35] op_sel_hi:[0,1]
	v_pk_mul_f32 v[18:19], v[30:31], v[18:19]
	v_lshlrev_b32_e32 v30, 16, v59
	v_and_b32_e32 v31, 0xffff0000, v59
	v_pk_add_f32 v[32:33], v[28:29], v[36:37] op_sel_hi:[0,1]
	v_pk_mul_f32 v[30:31], v[32:33], v[30:31]
	v_cvt_pk_bf16_f32 v18, v18, v19
	v_cvt_pk_bf16_f32 v19, v30, v31
	ds_write_b64 v81, v[18:19] offset:128
	v_lshlrev_b32_e32 v18, 16, v60
	v_and_b32_e32 v19, 0xffff0000, v60
	v_pk_add_f32 v[30:31], v[28:29], v[38:39] op_sel_hi:[0,1]
	v_pk_mul_f32 v[18:19], v[30:31], v[18:19]
	ds_read2_b64 v[30:33], v81 offset0:24 offset1:28
	v_lshlrev_b32_e32 v34, 16, v61
	v_and_b32_e32 v35, 0xffff0000, v61
	v_pk_add_f32 v[36:37], v[28:29], v[40:41] op_sel_hi:[0,1]
	v_pk_mul_f32 v[34:35], v[36:37], v[34:35]
	v_cvt_pk_bf16_f32 v18, v18, v19
	v_cvt_pk_bf16_f32 v19, v34, v35
	ds_write_b64 v81, v[18:19] offset:160
	s_waitcnt lgkmcnt(0)
	v_lshlrev_b32_e32 v18, 16, v30
	v_and_b32_e32 v19, 0xffff0000, v30
	v_pk_add_f32 v[34:35], v[28:29], v[42:43] op_sel_hi:[0,1]
	v_pk_mul_f32 v[18:19], v[34:35], v[18:19]
	v_lshlrev_b32_e32 v30, 16, v31
	v_and_b32_e32 v31, 0xffff0000, v31
	v_pk_add_f32 v[34:35], v[28:29], v[44:45] op_sel_hi:[0,1]
	v_pk_mul_f32 v[30:31], v[34:35], v[30:31]
	v_cvt_pk_bf16_f32 v18, v18, v19
	v_cvt_pk_bf16_f32 v19, v30, v31
	ds_write_b64 v81, v[18:19] offset:192
	v_lshlrev_b32_e32 v18, 16, v32
	v_and_b32_e32 v19, 0xffff0000, v32
	v_pk_add_f32 v[30:31], v[28:29], v[46:47] op_sel_hi:[0,1]
	v_pk_mul_f32 v[18:19], v[30:31], v[18:19]
	v_lshlrev_b32_e32 v34, 16, v33
	v_and_b32_e32 v35, 0xffff0000, v33
	ds_read2_b64 v[30:33], v81 offset0:32 offset1:36
	v_pk_add_f32 v[36:37], v[28:29], v[48:49] op_sel_hi:[0,1]
	v_pk_mul_f32 v[34:35], v[36:37], v[34:35]
	v_cvt_pk_bf16_f32 v18, v18, v19
	v_cvt_pk_bf16_f32 v19, v34, v35
	ds_write_b64 v81, v[18:19] offset:224
	s_waitcnt lgkmcnt(0)
	v_lshlrev_b32_e32 v18, 16, v30
	v_and_b32_e32 v19, 0xffff0000, v30
	v_pk_add_f32 v[34:35], v[28:29], v[50:51] op_sel_hi:[0,1]
	v_pk_mul_f32 v[18:19], v[34:35], v[18:19]
	v_lshlrev_b32_e32 v30, 16, v31
	v_and_b32_e32 v31, 0xffff0000, v31
	v_pk_add_f32 v[34:35], v[28:29], v[52:53] op_sel_hi:[0,1]
	v_pk_mul_f32 v[30:31], v[34:35], v[30:31]
	v_cvt_pk_bf16_f32 v18, v18, v19
	v_cvt_pk_bf16_f32 v19, v30, v31
	ds_read2_b64 v[34:37], v81 offset0:40 offset1:44
	ds_write_b64 v81, v[18:19] offset:256
	v_lshlrev_b32_e32 v18, 16, v32
	v_and_b32_e32 v19, 0xffff0000, v32
	v_pk_add_f32 v[30:31], v[28:29], v[54:55] op_sel_hi:[0,1]
	v_pk_mul_f32 v[18:19], v[30:31], v[18:19]
	v_lshlrev_b32_e32 v30, 16, v33
	v_and_b32_e32 v31, 0xffff0000, v33
	v_pk_add_f32 v[32:33], v[28:29], v[56:57] op_sel_hi:[0,1]
	v_pk_mul_f32 v[30:31], v[32:33], v[30:31]
	v_cvt_pk_bf16_f32 v18, v18, v19
	v_cvt_pk_bf16_f32 v19, v30, v31
	ds_write_b64 v81, v[18:19] offset:288
	s_waitcnt lgkmcnt(0)
	v_lshlrev_b32_e32 v18, 16, v34
	v_and_b32_e32 v19, 0xffff0000, v34
	v_pk_add_f32 v[24:25], v[28:29], v[24:25] op_sel_hi:[0,1]
	v_pk_mul_f32 v[18:19], v[24:25], v[18:19]
	v_lshlrev_b32_e32 v24, 16, v35
	v_and_b32_e32 v25, 0xffff0000, v35
	v_pk_add_f32 v[26:27], v[28:29], v[26:27] op_sel_hi:[0,1]
	v_pk_mul_f32 v[24:25], v[26:27], v[24:25]
	v_cvt_pk_bf16_f32 v18, v18, v19
	v_cvt_pk_bf16_f32 v19, v24, v25
	ds_write_b64 v81, v[18:19] offset:320
	v_lshlrev_b32_e32 v18, 16, v36
	v_and_b32_e32 v19, 0xffff0000, v36
	v_pk_add_f32 v[20:21], v[28:29], v[20:21] op_sel_hi:[0,1]
	v_pk_mul_f32 v[18:19], v[20:21], v[18:19]
	v_lshlrev_b32_e32 v26, 16, v37
	v_cvt_pk_bf16_f32 v24, v18, v19
	ds_read2_b64 v[18:21], v81 offset0:48 offset1:52
	v_and_b32_e32 v27, 0xffff0000, v37
	v_pk_add_f32 v[22:23], v[28:29], v[22:23] op_sel_hi:[0,1]
	v_pk_mul_f32 v[22:23], v[22:23], v[26:27]
	v_pk_add_f32 v[12:13], v[28:29], v[12:13] op_sel_hi:[0,1]
	v_cvt_pk_bf16_f32 v25, v22, v23
	s_waitcnt lgkmcnt(0)
	v_lshlrev_b32_e32 v22, 16, v18
	v_and_b32_e32 v23, 0xffff0000, v18
	v_lshlrev_b32_e32 v18, 16, v19
	v_and_b32_e32 v19, 0xffff0000, v19
	v_pk_add_f32 v[14:15], v[28:29], v[14:15] op_sel_hi:[0,1]
	v_pk_mul_f32 v[12:13], v[12:13], v[22:23]
	v_pk_mul_f32 v[14:15], v[14:15], v[18:19]
	v_cvt_pk_bf16_f32 v12, v12, v13
	v_cvt_pk_bf16_f32 v13, v14, v15
	ds_write_b64 v81, v[12:13] offset:384
	v_lshlrev_b32_e32 v12, 16, v20
	v_and_b32_e32 v13, 0xffff0000, v20
	v_pk_add_f32 v[8:9], v[28:29], v[8:9] op_sel_hi:[0,1]
	v_pk_mul_f32 v[8:9], v[8:9], v[12:13]
	ds_read2_b64 v[12:15], v81 offset0:56 offset1:60
	v_lshlrev_b32_e32 v18, 16, v21
	v_and_b32_e32 v19, 0xffff0000, v21
	v_pk_add_f32 v[10:11], v[28:29], v[10:11] op_sel_hi:[0,1]
	v_pk_mul_f32 v[10:11], v[10:11], v[18:19]
	v_cvt_pk_bf16_f32 v8, v8, v9
	v_cvt_pk_bf16_f32 v9, v10, v11
	ds_write_b64 v81, v[8:9] offset:416
	s_waitcnt lgkmcnt(0)
	v_lshlrev_b32_e32 v8, 16, v12
	v_and_b32_e32 v9, 0xffff0000, v12
	v_pk_add_f32 v[4:5], v[28:29], v[4:5] op_sel_hi:[0,1]
	v_pk_mul_f32 v[4:5], v[4:5], v[8:9]
	v_lshlrev_b32_e32 v8, 16, v13
	v_and_b32_e32 v9, 0xffff0000, v13
	v_pk_add_f32 v[6:7], v[28:29], v[6:7] op_sel_hi:[0,1]
	v_pk_mul_f32 v[6:7], v[6:7], v[8:9]
	v_cvt_pk_bf16_f32 v4, v4, v5
	v_cvt_pk_bf16_f32 v5, v6, v7
	ds_write_b64 v81, v[4:5] offset:448
	v_lshlrev_b32_e32 v4, 16, v14
	v_and_b32_e32 v5, 0xffff0000, v14
	v_pk_add_f32 v[0:1], v[28:29], v[0:1] op_sel_hi:[0,1]
	v_pk_mul_f32 v[0:1], v[0:1], v[4:5]
	v_lshlrev_b32_e32 v4, 16, v15
	v_and_b32_e32 v5, 0xffff0000, v15
	v_pk_add_f32 v[2:3], v[28:29], v[2:3] op_sel_hi:[0,1]
	v_pk_mul_f32 v[2:3], v[2:3], v[4:5]
	s_add_i32 s3, s3, s94
	s_add_i32 s2, s2, s30
	v_cvt_pk_bf16_f32 v0, v0, v1
	v_cvt_pk_bf16_f32 v1, v2, v3
	s_cmpk_gt_i32 s3, 0x1ff
	ds_write_b64 v81, v[24:25] offset:352
	ds_write_b64 v81, v[0:1] offset:480
	v_readfirstlane_b32 s98, v16
	v_readfirstlane_b32 s99, v17
	v_readfirstlane_b32 s100, v81
	s_nop 0
	v_add_u32_e32 v250, s100, v249
	s_waitcnt lgkmcnt(0)
	ds_read_b128 v[0:3], v250
	ds_read_b128 v[4:7], v250 offset:1088
	ds_read_b128 v[8:11], v250 offset:2176
	ds_read_b128 v[12:15], v250 offset:3264
	ds_read_b128 v[16:19], v250 offset:4352
	ds_read_b128 v[20:23], v250 offset:5440
	ds_read_b128 v[24:27], v250 offset:6528
	ds_read_b128 v[28:31], v250 offset:7616
	s_waitcnt lgkmcnt(7)
	global_store_dwordx4 v248, v[0:3], s[98:99] nt
	s_waitcnt lgkmcnt(6)
	s_add_u32 s98, s98, 0x2100
	s_addc_u32 s99, s99, 0
	global_store_dwordx4 v248, v[4:7], s[98:99] nt
	s_waitcnt lgkmcnt(5)
	s_add_u32 s98, s98, 0x2100
	s_addc_u32 s99, s99, 0
	global_store_dwordx4 v248, v[8:11], s[98:99] nt
	s_waitcnt lgkmcnt(4)
	s_add_u32 s98, s98, 0x2100
	s_addc_u32 s99, s99, 0
	global_store_dwordx4 v248, v[12:15], s[98:99] nt
	s_waitcnt lgkmcnt(3)
	s_add_u32 s98, s98, 0x2100
	s_addc_u32 s99, s99, 0
	global_store_dwordx4 v248, v[16:19], s[98:99] nt
	s_waitcnt lgkmcnt(2)
	s_add_u32 s98, s98, 0x2100
	s_addc_u32 s99, s99, 0
	global_store_dwordx4 v248, v[20:23], s[98:99] nt
	s_waitcnt lgkmcnt(1)
	s_add_u32 s98, s98, 0x2100
	s_addc_u32 s99, s99, 0
	global_store_dwordx4 v248, v[24:27], s[98:99] nt
	s_waitcnt lgkmcnt(0)
	s_add_u32 s98, s98, 0x2100
	s_addc_u32 s99, s99, 0
	global_store_dwordx4 v248, v[28:31], s[98:99] nt
	s_cmpk_gt_i32 s3, 0x1ff
	s_barrier
	s_cbranch_scc0 .LBB0_125
